# v14: v13 + SLAB0 412->384 (exactly 2 weight slabs per workgroup in P0: no light/heavy imbalance; 28 slabs more in the P1 tail)
# baseline (speedup 1.0000x reference)
.LBB0_18:
	s_or_b64 exec, exec, s[24:25]
	s_lshl_b32 s4, s3, 7
	s_add_i32 s4, s4, 0
	s_lshl_b32 s63, s3, 9
	s_add_i32 s72, s4, 0x16000
	s_mov_b32 s7, 0
	s_cmpk_gt_i32 s2, 0x1ff
	v_lshlrev_b32_e32 v84, 2, v128
	s_waitcnt lgkmcnt(0)
	s_barrier
	s_cbranch_scc1 .LBB0_34
	s_lshl_b32 s5, s3, 5
	s_and_b32 s4, s63, 0x7ffff800
	s_and_b32 s5, s5, 0x60
	v_ashrrev_i32_e32 v0, 1, v128
	s_or_b32 s4, s4, s5
	v_and_b32_e32 v0, -4, v0
	v_and_b32_e32 v64, 28, v84
	v_add_u32_e32 v0, s4, v0
	v_lshlrev_b32_e32 v66, 2, v64
	v_mov_b32_e32 v67, 0
	v_lshl_add_u64 v[2:3], s[18:19], 0, v[66:67]
	s_mov_b64 s[26:27], 0xb8000
	v_ashrrev_i32_e32 v1, 31, v0
	v_lshl_add_u64 v[68:69], v[2:3], 0, s[26:27]
	v_lshl_add_u64 v[4:5], s[18:19], 0, v[0:1]
	s_mov_b64 s[26:27], 0x4c00000
	v_lshlrev_b32_e32 v1, 3, v128
	s_add_i32 s6, 0, 0x16000
	v_lshl_add_u64 v[70:71], v[4:5], 0, s[26:27]
	v_and_b32_e32 v4, 0xffffffc0, v1
	s_add_i32 s4, 0, 0x17000
	v_add_u32_e32 v86, s6, v66
	v_add_u32_e32 v1, s63, v4
	s_mov_b32 s6, 0xac00
	v_lshl_add_u32 v65, v0, 2, s4
	v_cmp_gt_u32_e64 s[4:5], 8, v128
	v_mad_i64_i32 v[72:73], s[26:27], v1, s6, 0
	s_and_b64 s[24:25], s[40:41], s[4:5]
	s_mov_b64 s[26:27], 0xa0000
	v_lshl_add_u64 v[74:75], v[2:3], 0, s[26:27]
	s_add_u32 s26, s18, s63
	s_addc_u32 s27, s19, 0
	v_ashrrev_i32_e32 v5, 31, v4
	v_lshl_add_u64 v[2:3], s[26:27], 0, v[4:5]
	s_mov_b64 s[26:27], 0x6c00000
	s_lshl_b32 s6, s2, 5
	v_writelane_b32 v247, s84, 1
	v_lshl_add_u64 v[76:77], v[2:3], 0, s[26:27]
	v_or_b32_e32 v1, s6, v64
	v_mov_b32_e32 v2, 0xfd000000
	v_writelane_b32 v247, s85, 2
	v_lshl_add_u32 v78, v1, 12, v2
	v_lshl_add_u32 v0, v0, 12, v1
	v_mov_b32_e32 v1, 0xffff4000
	v_writelane_b32 v247, s72, 3
	v_add_u32_e32 v85, s72, v66
	s_lshl_b32 s27, s64, 17
	v_lshl_add_u32 v80, v0, 2, v1
	s_lshl_b32 s38, s64, 7
	s_addk_i32 s6, 0xd000
	s_lshl_b32 s39, s64, 5
	s_mov_b32 s42, 0x204000
	s_mov_b32 s43, 0x42fe0000
	s_mov_b32 s44, 0xc0c0400
	s_mov_b32 s45, 0x5040100
	s_movk_i32 s46, 0x1000
	s_movk_i32 s47, 0x2000
	s_movk_i32 s48, 0x3000
	v_add_u32_e32 v87, 4, v65
	v_add_u32_e32 v88, 8, v65
	v_add_u32_e32 v89, 12, v65
	s_mov_b32 s49, 0xc1000
	s_mov_b32 s50, 0xcc000
	s_mov_b32 s51, 0xd7000
	s_mov_b32 s52, 0xe1000
	s_mov_b32 s53, 0xec000
	s_mov_b32 s54, 0xf7000
	s_mov_b32 s55, 0x102000
	s_mov_b32 s56, 0x10c000
	s_mov_b32 s57, 0x117000
	s_mov_b32 s58, 0x122000
	s_mov_b32 s59, 0x12d000
	s_mov_b32 s60, 0x137000
	s_mov_b32 s61, 0x142000
	s_mov_b32 s67, 0x14d000
	s_mov_b32 s69, 0x158000
	s_mov_b32 s70, 0x162000
	s_mov_b32 s71, 0x16d000
	s_mov_b32 s72, 0x178000
	s_mov_b32 s73, 0x183000
	s_mov_b32 s74, 0x18d000
	s_mov_b32 s75, 0x198000
	s_mov_b32 s76, 0x1a3000
	s_mov_b32 s77, 0x1ae000
	s_mov_b32 s78, 0x1b8000
	s_mov_b32 s79, 0x1c3000
	s_mov_b32 s80, 0x1ce000
	s_mov_b32 s81, 0x1d9000
	s_mov_b32 s82, 0x1e3000
	s_mov_b32 s83, 0x1ee000
	s_mov_b32 s84, 0x1f9000
	s_mov_b32 s85, 0x20e000
	s_mov_b32 s86, 0x219000
	s_mov_b32 s87, 0x224000
	s_mov_b32 s88, 0x22f000
	s_mov_b32 s89, 0x239000
	s_mov_b32 s90, 0x244000
	s_mov_b32 s91, 0x24f000
	s_mov_b32 s92, 0x25a000
	s_mov_b32 s93, 0x264000
	s_mov_b32 s94, 0x26f000
	s_mov_b32 s95, 0x27a000
	s_mov_b32 s96, 0x285000
	s_mov_b32 s97, 0x28f000
	s_mov_b32 s34, 0x29a000
	s_mov_b32 s35, 0x2a5000
	s_mov_b32 s62, s2
	s_mov_b32 s26, 0x3f808000
	s_branch .LBB0_22

.LBB0_21:
	s_add_i32 s62, s62, s64
	s_add_i32 s6, s6, s39
	v_add_u32_e32 v78, s27, v78
	s_cmpk_lt_i32 s62, 0x200
	v_add_u32_e32 v80, s38, v80
	s_cbranch_scc0 .LBB0_33
.LBB0_22:
	s_cmpk_gt_i32 s62, 0x17f
	s_mov_b64 s[28:29], -1
	s_cbranch_scc0 .LBB0_28
	v_mov_b32_e32 v81, v67
	v_lshl_add_u64 v[82:83], s[22:23], 0, v[80:81]
	v_add_co_u32_e32 v4, vcc, 0x200000, v82
	global_load_dwordx4 v[0:3], v80, s[22:23] nt
	s_nop 0
	v_addc_co_u32_e32 v5, vcc, 0, v83, vcc
	v_add_co_u32_e32 v8, vcc, 0x400000, v82
	global_load_dwordx4 v[4:7], v[4:5], off nt
	s_nop 0
	v_addc_co_u32_e32 v9, vcc, 0, v83, vcc
	global_load_dwordx4 v[12:15], v[8:9], off nt
	v_add_co_u32_e32 v8, vcc, 0x600000, v82
	ds_read2st64_b32 v[98:99], v65 offset0:12 offset1:14
	s_nop 0
	v_addc_co_u32_e32 v9, vcc, 0, v83, vcc
	global_load_dwordx4 v[36:39], v[8:9], off nt
	v_add_co_u32_e32 v8, vcc, 0x800000, v82
	ds_read2st64_b32 v[102:103], v65 offset0:20 offset1:22
	s_nop 0
	v_addc_co_u32_e32 v9, vcc, 0, v83, vcc
	v_add_co_u32_e32 v16, vcc, 0xa00000, v82
	global_load_dwordx4 v[8:11], v[8:9], off nt
	s_nop 0
	v_addc_co_u32_e32 v17, vcc, 0, v83, vcc
	v_add_co_u32_e32 v20, vcc, 0xc00000, v82
	global_load_dwordx4 v[16:19], v[16:17], off nt
	s_nop 0
	v_addc_co_u32_e32 v21, vcc, 0, v83, vcc
	global_load_dwordx4 v[40:43], v[20:21], off nt
	v_add_co_u32_e32 v20, vcc, 0xe00000, v82
	ds_read2st64_b32 v[92:93], v65 offset0:4 offset1:6
	s_nop 0
	v_addc_co_u32_e32 v21, vcc, 0, v83, vcc
	global_load_dwordx4 v[44:47], v[20:21], off nt
	v_add_co_u32_e32 v20, vcc, 0x1000000, v82
	s_waitcnt lgkmcnt(2)
	v_mul_f32_e32 v98, 0x3e000000, v98
	v_addc_co_u32_e32 v21, vcc, 0, v83, vcc
	v_add_co_u32_e32 v24, vcc, 0x1200000, v82
	global_load_dwordx4 v[20:23], v[20:21], off nt
	s_nop 0
	v_addc_co_u32_e32 v25, vcc, 0, v83, vcc
	v_add_co_u32_e32 v28, vcc, 0x1400000, v82
	global_load_dwordx4 v[24:27], v[24:25], off nt
	s_nop 0
	v_addc_co_u32_e32 v29, vcc, 0, v83, vcc
	global_load_dwordx4 v[48:51], v[28:29], off nt
	v_add_co_u32_e32 v28, vcc, 0x1600000, v82
	s_waitcnt lgkmcnt(1)
	v_mul_f32_e32 v102, 0x3e000000, v102
	v_addc_co_u32_e32 v29, vcc, 0, v83, vcc
	global_load_dwordx4 v[52:55], v[28:29], off nt
	v_add_co_u32_e32 v28, vcc, 0x1800000, v82
	ds_read2st64_b32 v[106:107], v65 offset0:28 offset1:30
	s_nop 0
	v_addc_co_u32_e32 v29, vcc, 0, v83, vcc
	v_add_co_u32_e32 v32, vcc, 0x1a00000, v82
	global_load_dwordx4 v[28:31], v[28:29], off nt
	s_nop 0
	v_addc_co_u32_e32 v33, vcc, 0, v83, vcc
	v_add_co_u32_e32 v56, vcc, 0x1c00000, v82
	global_load_dwordx4 v[32:35], v[32:33], off nt
	s_nop 0
	v_addc_co_u32_e32 v57, vcc, 0, v83, vcc
	v_add_co_u32_e32 v60, vcc, 0x1e00000, v82
	global_load_dwordx4 v[56:59], v[56:57], off nt
	s_nop 0
	v_addc_co_u32_e32 v61, vcc, 0, v83, vcc
	global_load_dwordx4 v[60:63], v[60:61], off nt
	s_waitcnt lgkmcnt(1)
	v_mul_f32_e32 v94, 0x3e000000, v93
	ds_read2st64_b32 v[90:91], v65 offset1:2
	s_waitcnt lgkmcnt(1)
	v_mul_f32_e32 v106, 0x3e000000, v106
	v_mul_f32_e32 v92, 0x3e000000, v92
	s_movk_i32 s28, 0x4000
	s_waitcnt lgkmcnt(0)
	v_mul_f32_e32 v66, 0x3e000000, v91
	v_mul_f32_e32 v90, 0x3e000000, v90
	s_waitcnt vmcnt(13)
	v_pk_mul_f32 v[14:15], v[14:15], v[92:93] op_sel_hi:[1,0]
	v_pk_mul_f32 v[12:13], v[12:13], v[92:93] op_sel_hi:[1,0]
	v_pk_fma_f32 v[92:93], v[2:3], v[90:91], v[14:15] op_sel_hi:[1,0,1]
	v_pk_fma_f32 v[2:3], v[2:3], v[90:91], v[14:15] op_sel_hi:[1,0,1] neg_lo:[0,0,1] neg_hi:[0,0,1]
	s_waitcnt vmcnt(12)
	v_pk_mul_f32 v[38:39], v[38:39], v[94:95] op_sel_hi:[1,0]
	v_pk_mul_f32 v[36:37], v[36:37], v[94:95] op_sel_hi:[1,0]
	ds_read2st64_b32 v[94:95], v65 offset0:8 offset1:10
	v_pk_fma_f32 v[14:15], v[4:5], v[66:67], v[36:37] op_sel_hi:[1,0,1]
	v_pk_fma_f32 v[4:5], v[4:5], v[66:67], v[36:37] op_sel_hi:[1,0,1] neg_lo:[0,0,1] neg_hi:[0,0,1]
	s_waitcnt lgkmcnt(0)
	v_mul_f32_e32 v94, 0x3e000000, v94
	v_mul_f32_e32 v96, 0x3e000000, v95
	s_waitcnt vmcnt(9)
	v_pk_mul_f32 v[42:43], v[42:43], v[98:99] op_sel_hi:[1,0]
	v_pk_mul_f32 v[40:41], v[40:41], v[98:99] op_sel_hi:[1,0]
	v_mul_f32_e32 v98, 0x3e000000, v99
	v_pk_fma_f32 v[36:37], v[10:11], v[94:95], v[42:43] op_sel_hi:[1,0,1]
	v_pk_fma_f32 v[10:11], v[10:11], v[94:95], v[42:43] op_sel_hi:[1,0,1] neg_lo:[0,0,1] neg_hi:[0,0,1]
	s_waitcnt vmcnt(8)
	v_pk_mul_f32 v[46:47], v[46:47], v[98:99] op_sel_hi:[1,0]
	v_pk_mul_f32 v[44:45], v[44:45], v[98:99] op_sel_hi:[1,0]
	ds_read2st64_b32 v[98:99], v65 offset0:16 offset1:18
	v_pk_fma_f32 v[42:43], v[16:17], v[96:97], v[44:45] op_sel_hi:[1,0,1]
	v_pk_fma_f32 v[16:17], v[16:17], v[96:97], v[44:45] op_sel_hi:[1,0,1] neg_lo:[0,0,1] neg_hi:[0,0,1]
	s_waitcnt lgkmcnt(0)
	v_mul_f32_e32 v98, 0x3e000000, v98
	v_mul_f32_e32 v100, 0x3e000000, v99
	s_waitcnt vmcnt(5)
	v_pk_mul_f32 v[50:51], v[50:51], v[102:103] op_sel_hi:[1,0]
	v_pk_mul_f32 v[48:49], v[48:49], v[102:103] op_sel_hi:[1,0]
	v_mul_f32_e32 v102, 0x3e000000, v103
	v_pk_fma_f32 v[44:45], v[22:23], v[98:99], v[50:51] op_sel_hi:[1,0,1]
	v_pk_fma_f32 v[22:23], v[22:23], v[98:99], v[50:51] op_sel_hi:[1,0,1] neg_lo:[0,0,1] neg_hi:[0,0,1]
	s_waitcnt vmcnt(4)
	v_pk_mul_f32 v[54:55], v[54:55], v[102:103] op_sel_hi:[1,0]
	v_pk_mul_f32 v[52:53], v[52:53], v[102:103] op_sel_hi:[1,0]
	ds_read2st64_b32 v[102:103], v65 offset0:24 offset1:26
	v_pk_fma_f32 v[50:51], v[24:25], v[100:101], v[52:53] op_sel_hi:[1,0,1]
	v_pk_fma_f32 v[24:25], v[24:25], v[100:101], v[52:53] op_sel_hi:[1,0,1] neg_lo:[0,0,1] neg_hi:[0,0,1]
	s_waitcnt lgkmcnt(0)
	v_mul_f32_e32 v102, 0x3e000000, v102
	v_mul_f32_e32 v104, 0x3e000000, v103
	s_waitcnt vmcnt(1)
	v_pk_mul_f32 v[58:59], v[58:59], v[106:107] op_sel_hi:[1,0]
	v_pk_mul_f32 v[56:57], v[56:57], v[106:107] op_sel_hi:[1,0]
	v_mul_f32_e32 v106, 0x3e000000, v107
	s_waitcnt vmcnt(0)
	v_pk_mul_f32 v[60:61], v[60:61], v[106:107] op_sel_hi:[1,0]
	v_pk_mul_f32 v[62:63], v[62:63], v[106:107] op_sel_hi:[1,0]
	v_pk_fma_f32 v[106:107], v[0:1], v[90:91], v[12:13] op_sel_hi:[1,0,1]
	v_pk_fma_f32 v[0:1], v[0:1], v[90:91], v[12:13] op_sel_hi:[1,0,1] neg_lo:[0,0,1] neg_hi:[0,0,1]
	v_pk_fma_f32 v[12:13], v[6:7], v[66:67], v[38:39] op_sel_hi:[1,0,1]
	v_pk_fma_f32 v[6:7], v[6:7], v[66:67], v[38:39] op_sel_hi:[1,0,1] neg_lo:[0,0,1] neg_hi:[0,0,1]
	v_pk_fma_f32 v[38:39], v[8:9], v[94:95], v[40:41] op_sel_hi:[1,0,1]
	v_pk_fma_f32 v[8:9], v[8:9], v[94:95], v[40:41] op_sel_hi:[1,0,1] neg_lo:[0,0,1] neg_hi:[0,0,1]
	v_pk_fma_f32 v[40:41], v[18:19], v[96:97], v[46:47] op_sel_hi:[1,0,1]
	v_pk_fma_f32 v[18:19], v[18:19], v[96:97], v[46:47] op_sel_hi:[1,0,1] neg_lo:[0,0,1] neg_hi:[0,0,1]
	v_pk_fma_f32 v[46:47], v[20:21], v[98:99], v[48:49] op_sel_hi:[1,0,1]
	v_pk_fma_f32 v[20:21], v[20:21], v[98:99], v[48:49] op_sel_hi:[1,0,1] neg_lo:[0,0,1] neg_hi:[0,0,1]
	v_pk_fma_f32 v[48:49], v[26:27], v[100:101], v[54:55] op_sel_hi:[1,0,1]
	v_pk_fma_f32 v[26:27], v[26:27], v[100:101], v[54:55] op_sel_hi:[1,0,1] neg_lo:[0,0,1] neg_hi:[0,0,1]
	v_pk_fma_f32 v[52:53], v[30:31], v[102:103], v[58:59] op_sel_hi:[1,0,1]
	v_pk_fma_f32 v[54:55], v[28:29], v[102:103], v[56:57] op_sel_hi:[1,0,1]
	v_pk_fma_f32 v[30:31], v[30:31], v[102:103], v[58:59] op_sel_hi:[1,0,1] neg_lo:[0,0,1] neg_hi:[0,0,1]
	v_pk_fma_f32 v[58:59], v[32:33], v[104:105], v[60:61] op_sel_hi:[1,0,1]
	v_pk_fma_f32 v[28:29], v[28:29], v[102:103], v[56:57] op_sel_hi:[1,0,1] neg_lo:[0,0,1] neg_hi:[0,0,1]
	v_pk_fma_f32 v[56:57], v[34:35], v[104:105], v[62:63] op_sel_hi:[1,0,1]
	v_pk_fma_f32 v[34:35], v[34:35], v[104:105], v[62:63] op_sel_hi:[1,0,1] neg_lo:[0,0,1] neg_hi:[0,0,1]
	v_pk_fma_f32 v[32:33], v[32:33], v[104:105], v[60:61] op_sel_hi:[1,0,1] neg_lo:[0,0,1] neg_hi:[0,0,1]
	v_pk_add_f32 v[60:61], v[92:93], v[36:37]
	v_pk_add_f32 v[62:63], v[106:107], v[38:39]
	v_sub_f32_e32 v37, v93, v37
	v_sub_f32_e32 v36, v92, v36
	v_pk_add_f32 v[92:93], v[14:15], v[42:43]
	v_sub_f32_e32 v15, v15, v43
	v_sub_f32_e32 v14, v14, v42
	v_pk_add_f32 v[42:43], v[0:1], v[8:9]
	v_sub_f32_e32 v1, v1, v9
	v_sub_f32_e32 v0, v0, v8
	v_pk_add_f32 v[8:9], v[6:7], v[18:19]
	v_sub_f32_e32 v7, v7, v19
	v_sub_f32_e32 v6, v6, v18
	v_pk_add_f32 v[18:19], v[46:47], v[54:55]
	v_sub_f32_e32 v47, v47, v55
	v_sub_f32_e32 v46, v46, v54
	v_pk_add_f32 v[54:55], v[50:51], v[58:59]
	v_pk_add_f32 v[90:91], v[12:13], v[40:41]
	v_sub_f32_e32 v13, v13, v41
	v_sub_f32_e32 v12, v12, v40
	v_pk_add_f32 v[40:41], v[2:3], v[10:11]
	v_sub_f32_e32 v3, v3, v11
	v_sub_f32_e32 v2, v2, v10
	v_pk_add_f32 v[10:11], v[4:5], v[16:17]
	v_sub_f32_e32 v5, v5, v17
	v_sub_f32_e32 v4, v4, v16
	v_pk_add_f32 v[16:17], v[44:45], v[52:53]
	v_sub_f32_e32 v45, v45, v53
	v_sub_f32_e32 v44, v44, v52
	v_pk_add_f32 v[52:53], v[48:49], v[56:57]
	v_sub_f32_e32 v49, v49, v57
	v_sub_f32_e32 v48, v48, v56
	v_sub_f32_e32 v51, v51, v59
	v_sub_f32_e32 v50, v50, v58
	v_pk_add_f32 v[56:57], v[22:23], v[30:31]
	v_pk_add_f32 v[58:59], v[20:21], v[28:29]
	v_sub_f32_e32 v23, v23, v31
	v_sub_f32_e32 v22, v22, v30
	v_sub_f32_e32 v21, v21, v29
	v_sub_f32_e32 v20, v20, v28
	v_pk_add_f32 v[28:29], v[26:27], v[34:35]
	v_pk_add_f32 v[30:31], v[24:25], v[32:33]
	v_sub_f32_e32 v27, v27, v35
	v_sub_f32_e32 v26, v26, v34
	v_sub_f32_e32 v25, v25, v33
	v_sub_f32_e32 v24, v24, v32
	v_pk_add_f32 v[34:35], v[62:63], v[18:19]
	v_sub_f32_e32 v62, v62, v18
	v_sub_f32_e32 v63, v63, v19
	v_pk_add_f32 v[18:19], v[92:93], v[54:55]
	v_sub_f32_e32 v39, v107, v39
	v_sub_f32_e32 v38, v106, v38
	v_pk_add_f32 v[32:33], v[60:61], v[16:17]
	v_sub_f32_e32 v60, v60, v16
	v_sub_f32_e32 v61, v61, v17
	v_pk_add_f32 v[16:17], v[90:91], v[52:53]
	v_sub_f32_e32 v66, v91, v53
	v_sub_f32_e32 v79, v90, v52
	v_sub_f32_e32 v81, v93, v55
	v_sub_f32_e32 v90, v92, v54
	v_pk_add_f32 v[52:53], v[40:41], v[56:57]
	v_pk_add_f32 v[54:55], v[42:43], v[58:59]
	v_sub_f32_e32 v56, v40, v56
	v_sub_f32_e32 v57, v41, v57
	v_sub_f32_e32 v58, v42, v58
	v_sub_f32_e32 v59, v43, v59
	v_pk_add_f32 v[40:41], v[8:9], v[28:29]
	v_pk_add_f32 v[42:43], v[10:11], v[30:31]
	v_sub_f32_e32 v92, v9, v29
	v_sub_f32_e32 v93, v8, v28
	v_pk_add_f32 v[8:9], v[36:37], v[44:45]
	v_sub_f32_e32 v36, v36, v44
	v_sub_f32_e32 v37, v37, v45
	v_pk_add_f32 v[28:29], v[12:13], v[48:49]
	v_sub_f32_e32 v44, v13, v49
	v_sub_f32_e32 v45, v12, v48
	v_pk_add_f32 v[12:13], v[2:3], v[22:23]
	v_sub_f32_e32 v22, v2, v22
	v_sub_f32_e32 v23, v3, v23
	v_pk_add_f32 v[2:3], v[4:5], v[24:25]
	v_sub_f32_e32 v4, v4, v24
	v_max3_f32 v24, |v34|, 0, |v18|
	v_sub_f32_e32 v104, v11, v31
	v_sub_f32_e32 v105, v10, v30
	v_pk_add_f32 v[10:11], v[38:39], v[46:47]
	v_sub_f32_e32 v38, v38, v46
	v_sub_f32_e32 v39, v39, v47
	v_pk_add_f32 v[30:31], v[14:15], v[50:51]
	v_sub_f32_e32 v46, v15, v51
	v_sub_f32_e32 v47, v14, v50
	v_pk_add_f32 v[14:15], v[0:1], v[20:21]
	v_sub_f32_e32 v20, v0, v20
	v_sub_f32_e32 v21, v1, v21
	v_pk_add_f32 v[0:1], v[6:7], v[26:27]
	v_sub_f32_e32 v6, v6, v26
	v_sub_f32_e32 v5, v5, v25
	v_cvt_pk_bf16_f32 v119, v34, v35
	v_cvt_pk_bf16_f32 v103, v32, v33
	v_max3_f32 v25, |v35|, 0, |v19|
	v_max3_f32 v26, |v32|, 0, |v16|
	v_cvt_pk_bf16_f32 v118, v18, v19
	v_cvt_pk_bf16_f32 v102, v16, v17
	v_max3_f32 v16, v24, |v54|, |v42|
	v_sub_f32_e32 v7, v7, v27
	v_max3_f32 v27, |v33|, 0, |v17|
	v_cvt_pk_bf16_f32 v117, v54, v55
	v_cvt_pk_bf16_f32 v101, v52, v53
	v_max3_f32 v17, v25, |v55|, |v43|
	v_max3_f32 v18, v26, |v52|, |v40|
	v_cvt_pk_bf16_f32 v116, v42, v43
	v_cvt_pk_bf16_f32 v100, v40, v41
	v_cvt_pk_bf16_f32 v115, v10, v11
	v_max3_f32 v10, v16, |v10|, |v30|
	v_max3_f32 v19, v27, |v53|, |v41|
	v_cvt_pk_bf16_f32 v99, v8, v9
	v_max3_f32 v11, v17, |v11|, |v31|
	v_max3_f32 v8, v18, |v8|, |v28|
	v_max3_f32 v10, v10, |v14|, |v2|
	v_max3_f32 v9, v19, |v9|, |v29|
	v_cvt_pk_bf16_f32 v114, v30, v31
	v_cvt_pk_bf16_f32 v98, v28, v29
	v_cvt_pk_bf16_f32 v113, v14, v15
	v_cvt_pk_bf16_f32 v97, v12, v13
	v_max3_f32 v11, v11, |v15|, |v3|
	v_max3_f32 v8, v8, |v12|, |v0|
	v_cvt_pk_bf16_f32 v112, v2, v3
	v_cvt_pk_bf16_f32 v96, v0, v1
	v_max3_f32 v0, v10, |v62|, |v90|
	v_max3_f32 v9, v9, |v13|, |v1|
	v_max3_f32 v1, v11, |v63|, |v81|
	v_max3_f32 v0, v0, |v58|, |v105|
	v_max3_f32 v2, v8, |v60|, |v79|
	v_max3_f32 v3, v9, |v61|, |v66|
	v_max3_f32 v1, v1, |v59|, |v104|
	v_max3_f32 v0, v0, |v38|, |v47|
	v_max3_f32 v2, v2, |v56|, |v93|
	v_max3_f32 v3, v3, |v57|, |v92|
	v_max3_f32 v1, v1, |v39|, |v46|
	v_max3_f32 v122, v0, |v20|, |v4|
	v_add_co_u32_e32 v0, vcc, s28, v82
	v_max3_f32 v2, v2, |v36|, |v45|
	v_max3_f32 v3, v3, |v37|, |v44|
	v_max3_f32 v121, v1, |v21|, |v5|
	v_addc_co_u32_e32 v1, vcc, 0, v83, vcc
	v_cvt_pk_bf16_f32 v111, v62, v63
	v_cvt_pk_bf16_f32 v95, v60, v61
	v_cvt_pk_bf16_f32 v110, v90, v81
	v_cvt_pk_bf16_f32 v94, v79, v66
	v_cvt_pk_bf16_f32 v106, v58, v59
	v_cvt_pk_bf16_f32 v91, v56, v57
	v_cvt_pk_bf16_f32 v107, v105, v104
	v_cvt_pk_bf16_f32 v92, v93, v92
	v_cvt_pk_bf16_f32 v104, v38, v39
	v_cvt_pk_bf16_f32 v66, v36, v37
	v_cvt_pk_bf16_f32 v108, v47, v46
	v_cvt_pk_bf16_f32 v93, v45, v44
	v_cvt_pk_bf16_f32 v105, v20, v21
	v_cvt_pk_bf16_f32 v81, v22, v23
	v_max3_f32 v120, v2, |v22|, |v6|
	v_max3_f32 v79, v3, |v23|, |v7|
	v_cvt_pk_bf16_f32 v109, v4, v5
	v_cvt_pk_bf16_f32 v90, v6, v7
	global_load_dwordx4 v[4:7], v[0:1], off nt
	v_add_co_u32_e32 v0, vcc, s42, v82
	s_mov_b32 s28, 0x404000
	s_nop 0
	v_addc_co_u32_e32 v1, vcc, 0, v83, vcc
	v_add_co_u32_e32 v8, vcc, s28, v82
	s_mov_b32 s28, 0x604000
	s_nop 0
	v_addc_co_u32_e32 v9, vcc, 0, v83, vcc
	v_add_co_u32_e32 v12, vcc, s28, v82
	s_mov_b32 s28, 0x804000
	s_nop 0
	v_addc_co_u32_e32 v13, vcc, 0, v83, vcc
	global_load_dwordx4 v[60:63], v[12:13], off nt
	v_add_co_u32_e32 v12, vcc, s28, v82
	s_mov_b32 s28, 0xa04000
	s_nop 0
	v_addc_co_u32_e32 v13, vcc, 0, v83, vcc
	global_load_dwordx4 v[16:19], v[12:13], off nt
	v_add_co_u32_e32 v12, vcc, s28, v82
	s_mov_b32 s28, 0xc04000
	s_nop 0
	v_addc_co_u32_e32 v13, vcc, 0, v83, vcc
	v_add_co_u32_e32 v20, vcc, s28, v82
	s_mov_b32 s28, 0xe04000
	s_nop 0
	v_addc_co_u32_e32 v21, vcc, 0, v83, vcc
	global_load_dwordx4 v[12:15], v[12:13], off nt
	ds_read2st64_b32 v[136:137], v87 offset0:12 offset1:14
	global_load_dwordx4 v[48:51], v[20:21], off nt
	v_add_co_u32_e32 v20, vcc, s28, v82
	s_mov_b32 s28, 0x1004000
	s_nop 0
	v_addc_co_u32_e32 v21, vcc, 0, v83, vcc
	global_load_dwordx4 v[56:59], v[20:21], off nt
	v_add_co_u32_e32 v20, vcc, s28, v82
	s_mov_b32 s28, 0x1204000
	s_nop 0
	v_addc_co_u32_e32 v21, vcc, 0, v83, vcc
	global_load_dwordx4 v[24:27], v[20:21], off nt
	v_add_co_u32_e32 v20, vcc, s28, v82
	s_mov_b32 s28, 0x1404000
	s_nop 0
	v_addc_co_u32_e32 v21, vcc, 0, v83, vcc
	v_add_co_u32_e32 v28, vcc, s28, v82
	s_mov_b32 s28, 0x1604000
	s_nop 0
	v_addc_co_u32_e32 v29, vcc, 0, v83, vcc
	global_load_dwordx4 v[20:23], v[20:21], off nt
	ds_read2st64_b32 v[140:141], v87 offset0:20 offset1:22
	global_load_dwordx4 v[44:47], v[28:29], off nt
	v_add_co_u32_e32 v28, vcc, s28, v82
	s_mov_b32 s28, 0x1804000
	s_nop 0
	v_addc_co_u32_e32 v29, vcc, 0, v83, vcc
	global_load_dwordx4 v[52:55], v[28:29], off nt
	v_add_co_u32_e32 v28, vcc, s28, v82
	s_mov_b32 s28, 0x1a04000
	s_nop 0
	v_addc_co_u32_e32 v29, vcc, 0, v83, vcc
	global_load_dwordx4 v[32:35], v[28:29], off nt
	v_add_co_u32_e32 v28, vcc, s28, v82
	s_mov_b32 s28, 0x1c04000
	s_nop 0
	v_addc_co_u32_e32 v29, vcc, 0, v83, vcc
	v_add_co_u32_e32 v36, vcc, s28, v82
	s_mov_b32 s28, 0x1e04000
	s_nop 0
	v_addc_co_u32_e32 v37, vcc, 0, v83, vcc
	v_add_co_u32_e32 v40, vcc, s28, v82
	global_load_dwordx4 v[28:31], v[28:29], off nt
	s_nop 0
	v_addc_co_u32_e32 v41, vcc, 0, v83, vcc
	global_load_dwordx4 v[36:39], v[36:37], off nt
	ds_read2st64_b32 v[130:131], v87 offset0:4 offset1:6
	global_load_dwordx4 v[0:3], v[0:1], off nt
	s_waitcnt lgkmcnt(2)
	v_mul_f32_e32 v136, 0x3e000000, v136
	global_load_dwordx4 v[8:11], v[8:9], off nt
	s_waitcnt lgkmcnt(1)
	v_mul_f32_e32 v140, 0x3e000000, v140
	global_load_dwordx4 v[40:43], v[40:41], off nt
	ds_read2st64_b32 v[144:145], v87 offset0:28 offset1:30
	s_waitcnt lgkmcnt(1)
	v_mul_f32_e32 v132, 0x3e000000, v131
	ds_read2_b32 v[124:125], v65 offset0:1 offset1:129
	s_waitcnt vmcnt(14)
	v_pk_mul_f32 v[62:63], v[62:63], v[132:133] op_sel_hi:[1,0]
	v_pk_mul_f32 v[60:61], v[60:61], v[132:133] op_sel_hi:[1,0]
	ds_read2st64_b32 v[132:133], v87 offset0:8 offset1:10
	s_waitcnt lgkmcnt(2)
	v_mul_f32_e32 v144, 0x3e000000, v144
	v_mul_f32_e32 v130, 0x3e000000, v130
	s_waitcnt lgkmcnt(1)
	v_mul_f32_e32 v126, 0x3e000000, v125
	v_mul_f32_e32 v124, 0x3e000000, v124
	s_waitcnt lgkmcnt(0)
	v_mul_f32_e32 v132, 0x3e000000, v132
	v_mul_f32_e32 v134, 0x3e000000, v133
	s_mov_b32 s28, 0x8000
	s_waitcnt vmcnt(11)
	v_pk_mul_f32 v[50:51], v[50:51], v[136:137] op_sel_hi:[1,0]
	v_pk_mul_f32 v[48:49], v[48:49], v[136:137] op_sel_hi:[1,0]
	v_mul_f32_e32 v136, 0x3e000000, v137
	s_waitcnt vmcnt(10)
	v_pk_mul_f32 v[58:59], v[58:59], v[136:137] op_sel_hi:[1,0]
	v_pk_mul_f32 v[56:57], v[56:57], v[136:137] op_sel_hi:[1,0]
	ds_read2st64_b32 v[136:137], v87 offset0:16 offset1:18
	s_waitcnt lgkmcnt(0)
	v_mul_f32_e32 v136, 0x3e000000, v136
	v_mul_f32_e32 v138, 0x3e000000, v137
	s_waitcnt vmcnt(7)
	v_pk_mul_f32 v[46:47], v[46:47], v[140:141] op_sel_hi:[1,0]
	v_pk_mul_f32 v[44:45], v[44:45], v[140:141] op_sel_hi:[1,0]
	v_mul_f32_e32 v140, 0x3e000000, v141
	s_waitcnt vmcnt(6)
	v_pk_mul_f32 v[54:55], v[54:55], v[140:141] op_sel_hi:[1,0]
	v_pk_mul_f32 v[52:53], v[52:53], v[140:141] op_sel_hi:[1,0]
	ds_read2st64_b32 v[140:141], v87 offset0:24 offset1:26
	s_waitcnt lgkmcnt(0)
	v_mul_f32_e32 v140, 0x3e000000, v140
	v_mul_f32_e32 v142, 0x3e000000, v141
	s_waitcnt vmcnt(3)
	v_pk_mul_f32 v[38:39], v[38:39], v[144:145] op_sel_hi:[1,0]
	v_pk_mul_f32 v[36:37], v[36:37], v[144:145] op_sel_hi:[1,0]
	v_mul_f32_e32 v144, 0x3e000000, v145
	s_waitcnt vmcnt(1)
	v_pk_mul_f32 v[10:11], v[10:11], v[130:131] op_sel_hi:[1,0]
	v_pk_mul_f32 v[8:9], v[8:9], v[130:131] op_sel_hi:[1,0]
	s_waitcnt vmcnt(0)
	v_pk_mul_f32 v[40:41], v[40:41], v[144:145] op_sel_hi:[1,0]
	v_pk_mul_f32 v[42:43], v[42:43], v[144:145] op_sel_hi:[1,0]
	v_pk_fma_f32 v[130:131], v[6:7], v[124:125], v[10:11] op_sel_hi:[1,0,1]
	v_pk_fma_f32 v[144:145], v[4:5], v[124:125], v[8:9] op_sel_hi:[1,0,1]
	v_pk_fma_f32 v[6:7], v[6:7], v[124:125], v[10:11] op_sel_hi:[1,0,1] neg_lo:[0,0,1] neg_hi:[0,0,1]
	v_pk_fma_f32 v[4:5], v[4:5], v[124:125], v[8:9] op_sel_hi:[1,0,1] neg_lo:[0,0,1] neg_hi:[0,0,1]
	v_pk_fma_f32 v[8:9], v[2:3], v[126:127], v[62:63] op_sel_hi:[1,0,1]
	v_pk_fma_f32 v[10:11], v[0:1], v[126:127], v[60:61] op_sel_hi:[1,0,1]
	v_pk_fma_f32 v[2:3], v[2:3], v[126:127], v[62:63] op_sel_hi:[1,0,1] neg_lo:[0,0,1] neg_hi:[0,0,1]
	v_pk_fma_f32 v[0:1], v[0:1], v[126:127], v[60:61] op_sel_hi:[1,0,1] neg_lo:[0,0,1] neg_hi:[0,0,1]
	v_pk_fma_f32 v[60:61], v[18:19], v[132:133], v[50:51] op_sel_hi:[1,0,1]
	v_pk_fma_f32 v[62:63], v[16:17], v[132:133], v[48:49] op_sel_hi:[1,0,1]
	v_pk_fma_f32 v[18:19], v[18:19], v[132:133], v[50:51] op_sel_hi:[1,0,1] neg_lo:[0,0,1] neg_hi:[0,0,1]
	v_pk_fma_f32 v[16:17], v[16:17], v[132:133], v[48:49] op_sel_hi:[1,0,1] neg_lo:[0,0,1] neg_hi:[0,0,1]
	v_pk_fma_f32 v[48:49], v[14:15], v[134:135], v[58:59] op_sel_hi:[1,0,1]
	v_pk_fma_f32 v[50:51], v[12:13], v[134:135], v[56:57] op_sel_hi:[1,0,1]
	v_pk_fma_f32 v[14:15], v[14:15], v[134:135], v[58:59] op_sel_hi:[1,0,1] neg_lo:[0,0,1] neg_hi:[0,0,1]
	v_pk_fma_f32 v[12:13], v[12:13], v[134:135], v[56:57] op_sel_hi:[1,0,1] neg_lo:[0,0,1] neg_hi:[0,0,1]
	v_pk_fma_f32 v[56:57], v[26:27], v[136:137], v[46:47] op_sel_hi:[1,0,1]
	v_pk_fma_f32 v[58:59], v[24:25], v[136:137], v[44:45] op_sel_hi:[1,0,1]
	v_pk_fma_f32 v[26:27], v[26:27], v[136:137], v[46:47] op_sel_hi:[1,0,1] neg_lo:[0,0,1] neg_hi:[0,0,1]
	v_pk_fma_f32 v[24:25], v[24:25], v[136:137], v[44:45] op_sel_hi:[1,0,1] neg_lo:[0,0,1] neg_hi:[0,0,1]
	v_pk_fma_f32 v[44:45], v[22:23], v[138:139], v[54:55] op_sel_hi:[1,0,1]
	v_pk_fma_f32 v[46:47], v[20:21], v[138:139], v[52:53] op_sel_hi:[1,0,1]
	v_pk_fma_f32 v[22:23], v[22:23], v[138:139], v[54:55] op_sel_hi:[1,0,1] neg_lo:[0,0,1] neg_hi:[0,0,1]
	v_pk_fma_f32 v[20:21], v[20:21], v[138:139], v[52:53] op_sel_hi:[1,0,1] neg_lo:[0,0,1] neg_hi:[0,0,1]
	v_pk_fma_f32 v[52:53], v[34:35], v[140:141], v[38:39] op_sel_hi:[1,0,1]
	v_pk_fma_f32 v[54:55], v[32:33], v[140:141], v[36:37] op_sel_hi:[1,0,1]
	v_pk_fma_f32 v[34:35], v[34:35], v[140:141], v[38:39] op_sel_hi:[1,0,1] neg_lo:[0,0,1] neg_hi:[0,0,1]
	v_pk_fma_f32 v[38:39], v[28:29], v[142:143], v[40:41] op_sel_hi:[1,0,1]
	v_pk_fma_f32 v[32:33], v[32:33], v[140:141], v[36:37] op_sel_hi:[1,0,1] neg_lo:[0,0,1] neg_hi:[0,0,1]
	v_pk_fma_f32 v[36:37], v[30:31], v[142:143], v[42:43] op_sel_hi:[1,0,1]
	v_pk_fma_f32 v[30:31], v[30:31], v[142:143], v[42:43] op_sel_hi:[1,0,1] neg_lo:[0,0,1] neg_hi:[0,0,1]
	v_pk_fma_f32 v[28:29], v[28:29], v[142:143], v[40:41] op_sel_hi:[1,0,1] neg_lo:[0,0,1] neg_hi:[0,0,1]
	v_pk_add_f32 v[42:43], v[144:145], v[62:63]
	v_pk_add_f32 v[126:127], v[10:11], v[50:51]
	v_sub_f32_e32 v11, v11, v51
	v_sub_f32_e32 v10, v10, v50
	v_pk_add_f32 v[50:51], v[4:5], v[16:17]
	v_sub_f32_e32 v5, v5, v17
	v_sub_f32_e32 v4, v4, v16
	v_pk_add_f32 v[16:17], v[2:3], v[14:15]
	v_sub_f32_e32 v3, v3, v15
	v_sub_f32_e32 v2, v2, v14
	v_pk_add_f32 v[14:15], v[58:59], v[54:55]
	v_sub_f32_e32 v55, v59, v55
	v_sub_f32_e32 v54, v58, v54
	v_pk_add_f32 v[58:59], v[46:47], v[38:39]
	v_pk_add_f32 v[40:41], v[130:131], v[60:61]
	v_pk_add_f32 v[124:125], v[8:9], v[48:49]
	v_sub_f32_e32 v9, v9, v49
	v_sub_f32_e32 v8, v8, v48
	v_pk_add_f32 v[48:49], v[6:7], v[18:19]
	v_sub_f32_e32 v7, v7, v19
	v_sub_f32_e32 v6, v6, v18
	v_pk_add_f32 v[18:19], v[0:1], v[12:13]
	v_sub_f32_e32 v1, v1, v13
	v_sub_f32_e32 v0, v0, v12
	v_pk_add_f32 v[12:13], v[56:57], v[52:53]
	v_sub_f32_e32 v53, v57, v53
	v_sub_f32_e32 v52, v56, v52
	v_pk_add_f32 v[56:57], v[44:45], v[36:37]
	v_sub_f32_e32 v37, v45, v37
	v_sub_f32_e32 v36, v44, v36
	v_sub_f32_e32 v39, v47, v39
	v_sub_f32_e32 v38, v46, v38
	v_pk_add_f32 v[44:45], v[26:27], v[34:35]
	v_pk_add_f32 v[46:47], v[24:25], v[32:33]
	v_sub_f32_e32 v27, v27, v35
	v_sub_f32_e32 v26, v26, v34
	v_sub_f32_e32 v25, v25, v33
	v_sub_f32_e32 v24, v24, v32
	v_pk_add_f32 v[32:33], v[22:23], v[30:31]
	v_pk_add_f32 v[34:35], v[20:21], v[28:29]
	v_sub_f32_e32 v23, v23, v31
	v_sub_f32_e32 v22, v22, v30
	v_sub_f32_e32 v21, v21, v29
	v_sub_f32_e32 v20, v20, v28
	v_pk_add_f32 v[30:31], v[42:43], v[14:15]
	v_sub_f32_e32 v138, v42, v14
	v_sub_f32_e32 v139, v43, v15
	v_pk_add_f32 v[14:15], v[126:127], v[58:59]
	v_sub_f32_e32 v63, v145, v63
	v_sub_f32_e32 v62, v144, v62
	v_pk_add_f32 v[28:29], v[40:41], v[12:13]
	v_sub_f32_e32 v123, v40, v12
	v_sub_f32_e32 v137, v41, v13
	v_pk_add_f32 v[12:13], v[124:125], v[56:57]
	v_sub_f32_e32 v57, v125, v57
	v_sub_f32_e32 v56, v124, v56
	v_pk_add_f32 v[40:41], v[48:49], v[44:45]
	v_pk_add_f32 v[42:43], v[50:51], v[46:47]
	v_sub_f32_e32 v48, v48, v44
	v_sub_f32_e32 v49, v49, v45
	v_sub_f32_e32 v50, v50, v46
	v_sub_f32_e32 v51, v51, v47
	v_pk_add_f32 v[44:45], v[16:17], v[32:33]
	v_pk_add_f32 v[46:47], v[18:19], v[34:35]
	v_sub_f32_e32 v124, v17, v33
	v_sub_f32_e32 v125, v16, v32
	v_pk_add_f32 v[32:33], v[8:9], v[36:37]
	v_sub_f32_e32 v37, v9, v37
	v_sub_f32_e32 v36, v8, v36
	v_pk_add_f32 v[8:9], v[6:7], v[26:27]
	v_sub_f32_e32 v26, v6, v26
	v_sub_f32_e32 v27, v7, v27
	v_pk_add_f32 v[6:7], v[0:1], v[20:21]
	v_sub_f32_e32 v0, v0, v20
	v_max3_f32 v20, v122, |v30|, |v14|
	v_sub_f32_e32 v61, v131, v61
	v_sub_f32_e32 v60, v130, v60
	v_sub_f32_e32 v140, v19, v35
	v_sub_f32_e32 v141, v18, v34
	v_pk_add_f32 v[18:19], v[62:63], v[54:55]
	v_pk_add_f32 v[34:35], v[10:11], v[38:39]
	v_sub_f32_e32 v39, v11, v39
	v_sub_f32_e32 v38, v10, v38
	v_pk_add_f32 v[10:11], v[4:5], v[24:25]
	v_sub_f32_e32 v24, v4, v24
	v_sub_f32_e32 v25, v5, v25
	v_pk_add_f32 v[4:5], v[2:3], v[22:23]
	v_sub_f32_e32 v2, v2, v22
	v_sub_f32_e32 v1, v1, v21
	v_cvt_pk_bf16_f32 v152, v30, v31
	v_cvt_pk_bf16_f32 v136, v28, v29
	v_max3_f32 v21, v121, |v31|, |v15|
	v_max3_f32 v22, v120, |v28|, |v12|
	v_cvt_pk_bf16_f32 v151, v14, v15
	v_cvt_pk_bf16_f32 v135, v12, v13
	v_max3_f32 v12, v20, |v42|, |v46|
	v_pk_add_f32 v[16:17], v[60:61], v[52:53]
	v_sub_f32_e32 v3, v3, v23
	v_max3_f32 v23, v79, |v29|, |v13|
	v_max3_f32 v13, v21, |v43|, |v47|
	v_max3_f32 v14, v22, |v40|, |v44|
	v_max3_f32 v12, v12, |v18|, |v34|
	v_sub_f32_e32 v58, v126, v58
	v_cvt_pk_bf16_f32 v150, v42, v43
	v_cvt_pk_bf16_f32 v134, v40, v41
	v_max3_f32 v15, v23, |v41|, |v45|
	v_cvt_pk_bf16_f32 v149, v46, v47
	v_cvt_pk_bf16_f32 v133, v44, v45
	v_cvt_pk_bf16_f32 v148, v18, v19
	v_cvt_pk_bf16_f32 v132, v16, v17
	v_max3_f32 v13, v13, |v19|, |v35|
	v_max3_f32 v14, v14, |v16|, |v32|
	v_cvt_pk_bf16_f32 v147, v34, v35
	v_cvt_pk_bf16_f32 v131, v32, v33
	v_cvt_pk_bf16_f32 v146, v10, v11
	v_max3_f32 v10, v12, |v10|, |v6|
	v_sub_f32_e32 v59, v127, v59
	v_max3_f32 v15, v15, |v17|, |v33|
	v_cvt_pk_bf16_f32 v130, v8, v9
	v_max3_f32 v11, v13, |v11|, |v7|
	v_max3_f32 v8, v14, |v8|, |v4|
	v_cvt_pk_bf16_f32 v145, v6, v7
	v_cvt_pk_bf16_f32 v129, v4, v5
	v_max3_f32 v4, v10, |v138|, |v58|
	v_sub_f32_e32 v54, v62, v54
	v_max3_f32 v9, v15, |v9|, |v5|
	v_max3_f32 v5, v11, |v139|, |v59|
	v_max3_f32 v4, v4, |v50|, |v141|
	v_sub_f32_e32 v55, v63, v55
	v_max3_f32 v6, v8, |v123|, |v56|
	v_max3_f32 v7, v9, |v137|, |v57|
	v_max3_f32 v5, v5, |v51|, |v140|
	v_max3_f32 v4, v4, |v54|, |v38|
	v_sub_f32_e32 v52, v60, v52
	v_sub_f32_e32 v53, v61, v53
	v_cvt_pk_bf16_f32 v144, v138, v139
	v_cvt_pk_bf16_f32 v127, v123, v137
	v_cvt_pk_bf16_f32 v143, v58, v59
	v_cvt_pk_bf16_f32 v126, v56, v57
	v_cvt_pk_bf16_f32 v139, v50, v51
	v_cvt_pk_bf16_f32 v122, v48, v49
	v_max3_f32 v6, v6, |v48|, |v125|
	v_max3_f32 v7, v7, |v49|, |v124|
	v_cvt_pk_bf16_f32 v140, v141, v140
	v_cvt_pk_bf16_f32 v124, v125, v124
	v_cvt_pk_bf16_f32 v137, v54, v55
	v_cvt_pk_bf16_f32 v120, v52, v53
	v_max3_f32 v5, v5, |v55|, |v39|
	v_cvt_pk_bf16_f32 v141, v38, v39
	v_cvt_pk_bf16_f32 v125, v36, v37
	v_cvt_pk_bf16_f32 v138, v24, v25
	v_cvt_pk_bf16_f32 v121, v26, v27
	v_max3_f32 v155, v4, |v24|, |v0|
	v_cvt_pk_bf16_f32 v142, v0, v1
	v_add_co_u32_e32 v0, vcc, s28, v82
	v_max3_f32 v6, v6, |v52|, |v36|
	v_max3_f32 v7, v7, |v53|, |v37|
	v_max3_f32 v154, v5, |v25|, |v1|
	v_addc_co_u32_e32 v1, vcc, 0, v83, vcc
	s_mov_b32 s28, 0x208000
	v_max3_f32 v153, v6, |v26|, |v2|
	v_max3_f32 v79, v7, |v27|, |v3|
	v_cvt_pk_bf16_f32 v123, v2, v3
	global_load_dwordx4 v[4:7], v[0:1], off nt
	v_add_co_u32_e32 v0, vcc, s28, v82
	s_mov_b32 s28, 0x408000
	s_nop 0
	v_addc_co_u32_e32 v1, vcc, 0, v83, vcc
	v_add_co_u32_e32 v8, vcc, s28, v82
	s_mov_b32 s28, 0x608000
	s_nop 0
	v_addc_co_u32_e32 v9, vcc, 0, v83, vcc
	v_add_co_u32_e32 v12, vcc, s28, v82
	s_mov_b32 s28, 0x808000
	s_nop 0
	v_addc_co_u32_e32 v13, vcc, 0, v83, vcc
	global_load_dwordx4 v[60:63], v[12:13], off nt
	v_add_co_u32_e32 v12, vcc, s28, v82
	s_mov_b32 s28, 0xa08000
	s_nop 0
	v_addc_co_u32_e32 v13, vcc, 0, v83, vcc
	global_load_dwordx4 v[16:19], v[12:13], off nt
	v_add_co_u32_e32 v12, vcc, s28, v82
	s_mov_b32 s28, 0xc08000
	s_nop 0
	v_addc_co_u32_e32 v13, vcc, 0, v83, vcc
	v_add_co_u32_e32 v20, vcc, s28, v82
	s_mov_b32 s28, 0xe08000
	s_nop 0
	v_addc_co_u32_e32 v21, vcc, 0, v83, vcc
	global_load_dwordx4 v[12:15], v[12:13], off nt
	ds_read2st64_b32 v[166:167], v88 offset0:12 offset1:14
	global_load_dwordx4 v[48:51], v[20:21], off nt
	v_add_co_u32_e32 v20, vcc, s28, v82
	s_mov_b32 s28, 0x1008000
	s_nop 0
	v_addc_co_u32_e32 v21, vcc, 0, v83, vcc
	global_load_dwordx4 v[56:59], v[20:21], off nt
	v_add_co_u32_e32 v20, vcc, s28, v82
	s_mov_b32 s28, 0x1208000
	s_nop 0
	v_addc_co_u32_e32 v21, vcc, 0, v83, vcc
	global_load_dwordx4 v[24:27], v[20:21], off nt
	v_add_co_u32_e32 v20, vcc, s28, v82
	s_mov_b32 s28, 0x1408000
	s_nop 0
	v_addc_co_u32_e32 v21, vcc, 0, v83, vcc
	v_add_co_u32_e32 v28, vcc, s28, v82
	s_mov_b32 s28, 0x1608000
	s_nop 0
	v_addc_co_u32_e32 v29, vcc, 0, v83, vcc
	global_load_dwordx4 v[20:23], v[20:21], off nt
	ds_read2st64_b32 v[170:171], v88 offset0:20 offset1:22
	global_load_dwordx4 v[44:47], v[28:29], off nt
	v_add_co_u32_e32 v28, vcc, s28, v82
	s_mov_b32 s28, 0x1808000
	s_nop 0
	v_addc_co_u32_e32 v29, vcc, 0, v83, vcc
	global_load_dwordx4 v[52:55], v[28:29], off nt
	v_add_co_u32_e32 v28, vcc, s28, v82
	s_mov_b32 s28, 0x1a08000
	s_nop 0
	v_addc_co_u32_e32 v29, vcc, 0, v83, vcc
	global_load_dwordx4 v[32:35], v[28:29], off nt
	v_add_co_u32_e32 v28, vcc, s28, v82
	s_mov_b32 s28, 0x1c08000
	s_nop 0
	v_addc_co_u32_e32 v29, vcc, 0, v83, vcc
	v_add_co_u32_e32 v36, vcc, s28, v82
	s_mov_b32 s28, 0x1e08000
	s_nop 0
	v_addc_co_u32_e32 v37, vcc, 0, v83, vcc
	v_add_co_u32_e32 v40, vcc, s28, v82
	global_load_dwordx4 v[28:31], v[28:29], off nt
	s_nop 0
	v_addc_co_u32_e32 v41, vcc, 0, v83, vcc
	global_load_dwordx4 v[36:39], v[36:37], off nt
	ds_read2st64_b32 v[160:161], v88 offset0:4 offset1:6
	global_load_dwordx4 v[0:3], v[0:1], off nt
	s_waitcnt lgkmcnt(2)
	v_mul_f32_e32 v166, 0x3e000000, v166
	global_load_dwordx4 v[8:11], v[8:9], off nt
	s_waitcnt lgkmcnt(1)
	v_mul_f32_e32 v170, 0x3e000000, v170
	global_load_dwordx4 v[40:43], v[40:41], off nt
	ds_read2st64_b32 v[174:175], v88 offset0:28 offset1:30
	s_waitcnt lgkmcnt(1)
	v_mul_f32_e32 v162, 0x3e000000, v161
	ds_read2_b32 v[156:157], v65 offset0:2 offset1:130
	s_waitcnt vmcnt(14)
	v_pk_mul_f32 v[62:63], v[62:63], v[162:163] op_sel_hi:[1,0]
	v_pk_mul_f32 v[60:61], v[60:61], v[162:163] op_sel_hi:[1,0]
	ds_read2st64_b32 v[162:163], v88 offset0:8 offset1:10
	s_waitcnt lgkmcnt(2)
	v_mul_f32_e32 v174, 0x3e000000, v174
	v_mul_f32_e32 v160, 0x3e000000, v160
	s_waitcnt lgkmcnt(1)
	v_mul_f32_e32 v158, 0x3e000000, v157
	v_mul_f32_e32 v156, 0x3e000000, v156
	s_waitcnt lgkmcnt(0)
	v_mul_f32_e32 v162, 0x3e000000, v162
	v_mul_f32_e32 v164, 0x3e000000, v163
	s_mov_b32 s28, 0xc000
	s_waitcnt vmcnt(11)
	v_pk_mul_f32 v[50:51], v[50:51], v[166:167] op_sel_hi:[1,0]
	v_pk_mul_f32 v[48:49], v[48:49], v[166:167] op_sel_hi:[1,0]
	v_mul_f32_e32 v166, 0x3e000000, v167
	s_waitcnt vmcnt(10)
	v_pk_mul_f32 v[58:59], v[58:59], v[166:167] op_sel_hi:[1,0]
	v_pk_mul_f32 v[56:57], v[56:57], v[166:167] op_sel_hi:[1,0]
	ds_read2st64_b32 v[166:167], v88 offset0:16 offset1:18
	s_waitcnt lgkmcnt(0)
	v_mul_f32_e32 v166, 0x3e000000, v166
	v_mul_f32_e32 v168, 0x3e000000, v167
	s_waitcnt vmcnt(7)
	v_pk_mul_f32 v[46:47], v[46:47], v[170:171] op_sel_hi:[1,0]
	v_pk_mul_f32 v[44:45], v[44:45], v[170:171] op_sel_hi:[1,0]
	v_mul_f32_e32 v170, 0x3e000000, v171
	s_waitcnt vmcnt(6)
	v_pk_mul_f32 v[54:55], v[54:55], v[170:171] op_sel_hi:[1,0]
	v_pk_mul_f32 v[52:53], v[52:53], v[170:171] op_sel_hi:[1,0]
	ds_read2st64_b32 v[170:171], v88 offset0:24 offset1:26
	s_waitcnt lgkmcnt(0)
	v_mul_f32_e32 v170, 0x3e000000, v170
	v_mul_f32_e32 v172, 0x3e000000, v171
	s_waitcnt vmcnt(3)
	v_pk_mul_f32 v[38:39], v[38:39], v[174:175] op_sel_hi:[1,0]
	v_pk_mul_f32 v[36:37], v[36:37], v[174:175] op_sel_hi:[1,0]
	v_mul_f32_e32 v174, 0x3e000000, v175
	s_waitcnt vmcnt(1)
	v_pk_mul_f32 v[10:11], v[10:11], v[160:161] op_sel_hi:[1,0]
	v_pk_mul_f32 v[8:9], v[8:9], v[160:161] op_sel_hi:[1,0]
	s_waitcnt vmcnt(0)
	v_pk_mul_f32 v[40:41], v[40:41], v[174:175] op_sel_hi:[1,0]
	v_pk_mul_f32 v[42:43], v[42:43], v[174:175] op_sel_hi:[1,0]
	v_pk_fma_f32 v[160:161], v[6:7], v[156:157], v[10:11] op_sel_hi:[1,0,1]
	v_pk_fma_f32 v[174:175], v[4:5], v[156:157], v[8:9] op_sel_hi:[1,0,1]
	v_pk_fma_f32 v[6:7], v[6:7], v[156:157], v[10:11] op_sel_hi:[1,0,1] neg_lo:[0,0,1] neg_hi:[0,0,1]
	v_pk_fma_f32 v[4:5], v[4:5], v[156:157], v[8:9] op_sel_hi:[1,0,1] neg_lo:[0,0,1] neg_hi:[0,0,1]
	v_pk_fma_f32 v[8:9], v[2:3], v[158:159], v[62:63] op_sel_hi:[1,0,1]
	v_pk_fma_f32 v[10:11], v[0:1], v[158:159], v[60:61] op_sel_hi:[1,0,1]
	v_pk_fma_f32 v[2:3], v[2:3], v[158:159], v[62:63] op_sel_hi:[1,0,1] neg_lo:[0,0,1] neg_hi:[0,0,1]
	v_pk_fma_f32 v[0:1], v[0:1], v[158:159], v[60:61] op_sel_hi:[1,0,1] neg_lo:[0,0,1] neg_hi:[0,0,1]
	v_pk_fma_f32 v[60:61], v[18:19], v[162:163], v[50:51] op_sel_hi:[1,0,1]
	v_pk_fma_f32 v[62:63], v[16:17], v[162:163], v[48:49] op_sel_hi:[1,0,1]
	v_pk_fma_f32 v[18:19], v[18:19], v[162:163], v[50:51] op_sel_hi:[1,0,1] neg_lo:[0,0,1] neg_hi:[0,0,1]
	v_pk_fma_f32 v[16:17], v[16:17], v[162:163], v[48:49] op_sel_hi:[1,0,1] neg_lo:[0,0,1] neg_hi:[0,0,1]
	v_pk_fma_f32 v[48:49], v[14:15], v[164:165], v[58:59] op_sel_hi:[1,0,1]
	v_pk_fma_f32 v[50:51], v[12:13], v[164:165], v[56:57] op_sel_hi:[1,0,1]
	v_pk_fma_f32 v[14:15], v[14:15], v[164:165], v[58:59] op_sel_hi:[1,0,1] neg_lo:[0,0,1] neg_hi:[0,0,1]
	v_pk_fma_f32 v[12:13], v[12:13], v[164:165], v[56:57] op_sel_hi:[1,0,1] neg_lo:[0,0,1] neg_hi:[0,0,1]
	v_pk_fma_f32 v[56:57], v[26:27], v[166:167], v[46:47] op_sel_hi:[1,0,1]
	v_pk_fma_f32 v[58:59], v[24:25], v[166:167], v[44:45] op_sel_hi:[1,0,1]
	v_pk_fma_f32 v[26:27], v[26:27], v[166:167], v[46:47] op_sel_hi:[1,0,1] neg_lo:[0,0,1] neg_hi:[0,0,1]
	v_pk_fma_f32 v[24:25], v[24:25], v[166:167], v[44:45] op_sel_hi:[1,0,1] neg_lo:[0,0,1] neg_hi:[0,0,1]
	v_pk_fma_f32 v[44:45], v[22:23], v[168:169], v[54:55] op_sel_hi:[1,0,1]
	v_pk_fma_f32 v[46:47], v[20:21], v[168:169], v[52:53] op_sel_hi:[1,0,1]
	v_pk_fma_f32 v[22:23], v[22:23], v[168:169], v[54:55] op_sel_hi:[1,0,1] neg_lo:[0,0,1] neg_hi:[0,0,1]
	v_pk_fma_f32 v[20:21], v[20:21], v[168:169], v[52:53] op_sel_hi:[1,0,1] neg_lo:[0,0,1] neg_hi:[0,0,1]
	v_pk_fma_f32 v[52:53], v[34:35], v[170:171], v[38:39] op_sel_hi:[1,0,1]
	v_pk_fma_f32 v[54:55], v[32:33], v[170:171], v[36:37] op_sel_hi:[1,0,1]
	v_pk_fma_f32 v[34:35], v[34:35], v[170:171], v[38:39] op_sel_hi:[1,0,1] neg_lo:[0,0,1] neg_hi:[0,0,1]
	v_pk_fma_f32 v[38:39], v[28:29], v[172:173], v[40:41] op_sel_hi:[1,0,1]
	v_pk_fma_f32 v[32:33], v[32:33], v[170:171], v[36:37] op_sel_hi:[1,0,1] neg_lo:[0,0,1] neg_hi:[0,0,1]
	v_pk_fma_f32 v[36:37], v[30:31], v[172:173], v[42:43] op_sel_hi:[1,0,1]
	v_pk_fma_f32 v[30:31], v[30:31], v[172:173], v[42:43] op_sel_hi:[1,0,1] neg_lo:[0,0,1] neg_hi:[0,0,1]
	v_pk_fma_f32 v[28:29], v[28:29], v[172:173], v[40:41] op_sel_hi:[1,0,1] neg_lo:[0,0,1] neg_hi:[0,0,1]
	v_pk_add_f32 v[42:43], v[174:175], v[62:63]
	v_pk_add_f32 v[158:159], v[10:11], v[50:51]
	v_sub_f32_e32 v11, v11, v51
	v_sub_f32_e32 v10, v10, v50
	v_pk_add_f32 v[50:51], v[4:5], v[16:17]
	v_sub_f32_e32 v5, v5, v17
	v_sub_f32_e32 v4, v4, v16
	v_pk_add_f32 v[16:17], v[2:3], v[14:15]
	v_sub_f32_e32 v3, v3, v15
	v_sub_f32_e32 v2, v2, v14
	v_pk_add_f32 v[14:15], v[58:59], v[54:55]
	v_sub_f32_e32 v55, v59, v55
	v_sub_f32_e32 v54, v58, v54
	v_pk_add_f32 v[58:59], v[46:47], v[38:39]
	v_pk_add_f32 v[40:41], v[160:161], v[60:61]
	v_pk_add_f32 v[156:157], v[8:9], v[48:49]
	v_sub_f32_e32 v9, v9, v49
	v_sub_f32_e32 v8, v8, v48
	v_pk_add_f32 v[48:49], v[6:7], v[18:19]
	v_sub_f32_e32 v7, v7, v19
	v_sub_f32_e32 v6, v6, v18
	v_pk_add_f32 v[18:19], v[0:1], v[12:13]
	v_sub_f32_e32 v1, v1, v13
	v_sub_f32_e32 v0, v0, v12
	v_pk_add_f32 v[12:13], v[56:57], v[52:53]
	v_sub_f32_e32 v53, v57, v53
	v_sub_f32_e32 v52, v56, v52
	v_pk_add_f32 v[56:57], v[44:45], v[36:37]
	v_sub_f32_e32 v37, v45, v37
	v_sub_f32_e32 v36, v44, v36
	v_sub_f32_e32 v39, v47, v39
	v_sub_f32_e32 v38, v46, v38
	v_pk_add_f32 v[44:45], v[26:27], v[34:35]
	v_pk_add_f32 v[46:47], v[24:25], v[32:33]
	v_sub_f32_e32 v27, v27, v35
	v_sub_f32_e32 v26, v26, v34
	v_sub_f32_e32 v25, v25, v33
	v_sub_f32_e32 v24, v24, v32
	v_pk_add_f32 v[32:33], v[22:23], v[30:31]
	v_pk_add_f32 v[34:35], v[20:21], v[28:29]
	v_sub_f32_e32 v23, v23, v31
	v_sub_f32_e32 v22, v22, v30
	v_sub_f32_e32 v21, v21, v29
	v_sub_f32_e32 v20, v20, v28
	v_pk_add_f32 v[30:31], v[42:43], v[14:15]
	v_sub_f32_e32 v171, v42, v14
	v_sub_f32_e32 v172, v43, v15
	v_pk_add_f32 v[14:15], v[158:159], v[58:59]
	v_sub_f32_e32 v63, v175, v63
	v_sub_f32_e32 v62, v174, v62
	v_pk_add_f32 v[28:29], v[40:41], v[12:13]
	v_sub_f32_e32 v169, v40, v12
	v_sub_f32_e32 v170, v41, v13
	v_pk_add_f32 v[12:13], v[156:157], v[56:57]
	v_sub_f32_e32 v57, v157, v57
	v_sub_f32_e32 v56, v156, v56
	v_pk_add_f32 v[40:41], v[48:49], v[44:45]
	v_pk_add_f32 v[42:43], v[50:51], v[46:47]
	v_sub_f32_e32 v48, v48, v44
	v_sub_f32_e32 v49, v49, v45
	v_sub_f32_e32 v50, v50, v46
	v_sub_f32_e32 v51, v51, v47
	v_pk_add_f32 v[44:45], v[16:17], v[32:33]
	v_pk_add_f32 v[46:47], v[18:19], v[34:35]
	v_sub_f32_e32 v156, v17, v33
	v_sub_f32_e32 v157, v16, v32
	v_pk_add_f32 v[32:33], v[8:9], v[36:37]
	v_sub_f32_e32 v37, v9, v37
	v_sub_f32_e32 v36, v8, v36
	v_pk_add_f32 v[8:9], v[6:7], v[26:27]
	v_sub_f32_e32 v26, v6, v26
	v_sub_f32_e32 v27, v7, v27
	v_pk_add_f32 v[6:7], v[0:1], v[20:21]
	v_sub_f32_e32 v0, v0, v20
	v_max3_f32 v20, v155, |v30|, |v14|
	v_sub_f32_e32 v61, v161, v61
	v_sub_f32_e32 v60, v160, v60
	v_sub_f32_e32 v58, v158, v58
	v_sub_f32_e32 v158, v19, v35
	v_sub_f32_e32 v173, v18, v34
	v_pk_add_f32 v[18:19], v[62:63], v[54:55]
	v_pk_add_f32 v[34:35], v[10:11], v[38:39]
	v_sub_f32_e32 v39, v11, v39
	v_sub_f32_e32 v38, v10, v38
	v_pk_add_f32 v[10:11], v[4:5], v[24:25]
	v_sub_f32_e32 v24, v4, v24
	v_sub_f32_e32 v25, v5, v25
	v_pk_add_f32 v[4:5], v[2:3], v[22:23]
	v_sub_f32_e32 v2, v2, v22
	v_sub_f32_e32 v1, v1, v21
	v_cvt_pk_bf16_f32 v184, v30, v31
	v_cvt_pk_bf16_f32 v168, v28, v29
	v_max3_f32 v21, v154, |v31|, |v15|
	v_max3_f32 v22, v153, |v28|, |v12|
	v_cvt_pk_bf16_f32 v183, v14, v15
	v_cvt_pk_bf16_f32 v167, v12, v13
	v_max3_f32 v12, v20, |v42|, |v46|
	v_pk_add_f32 v[16:17], v[60:61], v[52:53]
	v_sub_f32_e32 v3, v3, v23
	v_max3_f32 v23, v79, |v29|, |v13|
	v_max3_f32 v13, v21, |v43|, |v47|
	v_max3_f32 v14, v22, |v40|, |v44|
	v_max3_f32 v12, v12, |v18|, |v34|
	v_cvt_pk_bf16_f32 v182, v42, v43
	v_cvt_pk_bf16_f32 v166, v40, v41
	v_max3_f32 v15, v23, |v41|, |v45|
	v_cvt_pk_bf16_f32 v181, v46, v47
	v_cvt_pk_bf16_f32 v165, v44, v45
	v_cvt_pk_bf16_f32 v180, v18, v19
	v_cvt_pk_bf16_f32 v164, v16, v17
	v_max3_f32 v13, v13, |v19|, |v35|
	v_max3_f32 v14, v14, |v16|, |v32|
	v_cvt_pk_bf16_f32 v179, v34, v35
	v_cvt_pk_bf16_f32 v163, v32, v33
	v_cvt_pk_bf16_f32 v178, v10, v11
	v_max3_f32 v10, v12, |v10|, |v6|
	v_sub_f32_e32 v59, v159, v59
	v_max3_f32 v15, v15, |v17|, |v33|
	v_cvt_pk_bf16_f32 v162, v8, v9
	v_max3_f32 v11, v13, |v11|, |v7|
	v_max3_f32 v8, v14, |v8|, |v4|
	v_cvt_pk_bf16_f32 v177, v6, v7
	v_cvt_pk_bf16_f32 v161, v4, v5
	v_max3_f32 v4, v10, |v171|, |v58|
	v_sub_f32_e32 v54, v62, v54
	v_max3_f32 v9, v15, |v9|, |v5|
	v_max3_f32 v5, v11, |v172|, |v59|
	v_max3_f32 v4, v4, |v50|, |v173|
	v_sub_f32_e32 v55, v63, v55
	v_max3_f32 v6, v8, |v169|, |v56|
	v_max3_f32 v7, v9, |v170|, |v57|
	v_max3_f32 v5, v5, |v51|, |v158|
	v_max3_f32 v4, v4, |v54|, |v38|
	v_sub_f32_e32 v52, v60, v52
	v_sub_f32_e32 v53, v61, v53
	v_cvt_pk_bf16_f32 v176, v171, v172
	v_cvt_pk_bf16_f32 v160, v169, v170
	v_cvt_pk_bf16_f32 v175, v58, v59
	v_cvt_pk_bf16_f32 v159, v56, v57
	v_cvt_pk_bf16_f32 v171, v50, v51
	v_cvt_pk_bf16_f32 v155, v48, v49
	v_max3_f32 v6, v6, |v48|, |v157|
	v_max3_f32 v7, v7, |v49|, |v156|
	v_cvt_pk_bf16_f32 v172, v173, v158
	v_cvt_pk_bf16_f32 v156, v157, v156
	v_cvt_pk_bf16_f32 v169, v54, v55
	v_cvt_pk_bf16_f32 v153, v52, v53
	v_max3_f32 v5, v5, |v55|, |v39|
	v_cvt_pk_bf16_f32 v173, v38, v39
	v_cvt_pk_bf16_f32 v157, v36, v37
	v_cvt_pk_bf16_f32 v170, v24, v25
	v_cvt_pk_bf16_f32 v154, v26, v27
	v_max3_f32 v187, v4, |v24|, |v0|
	v_cvt_pk_bf16_f32 v174, v0, v1
	v_add_co_u32_e32 v0, vcc, s28, v82
	v_max3_f32 v6, v6, |v52|, |v36|
	v_max3_f32 v7, v7, |v53|, |v37|
	v_max3_f32 v186, v5, |v25|, |v1|
	v_addc_co_u32_e32 v1, vcc, 0, v83, vcc
	s_mov_b32 s28, 0x20c000
	v_max3_f32 v185, v6, |v26|, |v2|
	v_max3_f32 v79, v7, |v27|, |v3|
	v_cvt_pk_bf16_f32 v158, v2, v3
	global_load_dwordx4 v[4:7], v[0:1], off nt
	v_add_co_u32_e32 v0, vcc, s28, v82
	s_mov_b32 s28, 0x40c000
	s_nop 0
	v_addc_co_u32_e32 v1, vcc, 0, v83, vcc
	v_add_co_u32_e32 v8, vcc, s28, v82
	s_mov_b32 s28, 0x60c000
	s_nop 0
	v_addc_co_u32_e32 v9, vcc, 0, v83, vcc
	v_add_co_u32_e32 v12, vcc, s28, v82
	s_mov_b32 s28, 0x80c000
	s_nop 0
	v_addc_co_u32_e32 v13, vcc, 0, v83, vcc
	global_load_dwordx4 v[60:63], v[12:13], off nt
	v_add_co_u32_e32 v12, vcc, s28, v82
	s_mov_b32 s28, 0xa0c000
	s_nop 0
	v_addc_co_u32_e32 v13, vcc, 0, v83, vcc
	global_load_dwordx4 v[16:19], v[12:13], off nt
	v_add_co_u32_e32 v12, vcc, s28, v82
	s_mov_b32 s28, 0xc0c000
	s_nop 0
	v_addc_co_u32_e32 v13, vcc, 0, v83, vcc
	v_add_co_u32_e32 v20, vcc, s28, v82
	s_mov_b32 s28, 0xe0c000
	s_nop 0
	v_addc_co_u32_e32 v21, vcc, 0, v83, vcc
	global_load_dwordx4 v[12:15], v[12:13], off nt
	ds_read2st64_b32 v[196:197], v89 offset0:12 offset1:14
	global_load_dwordx4 v[48:51], v[20:21], off nt
	v_add_co_u32_e32 v20, vcc, s28, v82
	s_mov_b32 s28, 0x100c000
	s_nop 0
	v_addc_co_u32_e32 v21, vcc, 0, v83, vcc
	global_load_dwordx4 v[56:59], v[20:21], off nt
	v_add_co_u32_e32 v20, vcc, s28, v82
	s_mov_b32 s28, 0x120c000
	s_nop 0
	v_addc_co_u32_e32 v21, vcc, 0, v83, vcc
	global_load_dwordx4 v[24:27], v[20:21], off nt
	v_add_co_u32_e32 v20, vcc, s28, v82
	s_mov_b32 s28, 0x140c000
	s_nop 0
	v_addc_co_u32_e32 v21, vcc, 0, v83, vcc
	v_add_co_u32_e32 v28, vcc, s28, v82
	s_mov_b32 s28, 0x160c000
	s_nop 0
	v_addc_co_u32_e32 v29, vcc, 0, v83, vcc
	global_load_dwordx4 v[20:23], v[20:21], off nt
	ds_read2st64_b32 v[200:201], v89 offset0:20 offset1:22
	global_load_dwordx4 v[44:47], v[28:29], off nt
	v_add_co_u32_e32 v28, vcc, s28, v82
	s_mov_b32 s28, 0x180c000
	s_nop 0
	v_addc_co_u32_e32 v29, vcc, 0, v83, vcc
	global_load_dwordx4 v[52:55], v[28:29], off nt
	v_add_co_u32_e32 v28, vcc, s28, v82
	s_mov_b32 s28, 0x1a0c000
	s_nop 0
	v_addc_co_u32_e32 v29, vcc, 0, v83, vcc
	global_load_dwordx4 v[32:35], v[28:29], off nt
	v_add_co_u32_e32 v28, vcc, s28, v82
	s_mov_b32 s28, 0x1c0c000
	s_nop 0
	v_addc_co_u32_e32 v29, vcc, 0, v83, vcc
	v_add_co_u32_e32 v36, vcc, s28, v82
	s_mov_b32 s28, 0x1e0c000
	s_nop 0
	v_addc_co_u32_e32 v37, vcc, 0, v83, vcc
	v_add_co_u32_e32 v40, vcc, s28, v82
	global_load_dwordx4 v[28:31], v[28:29], off nt
	s_nop 0
	v_addc_co_u32_e32 v41, vcc, 0, v83, vcc
	global_load_dwordx4 v[36:39], v[36:37], off nt
	ds_read2st64_b32 v[190:191], v89 offset0:4 offset1:6
	global_load_dwordx4 v[0:3], v[0:1], off nt
	s_waitcnt lgkmcnt(2)
	v_mul_f32_e32 v196, 0x3e000000, v196
	global_load_dwordx4 v[8:11], v[8:9], off nt
	s_waitcnt lgkmcnt(1)
	v_mul_f32_e32 v200, 0x3e000000, v200
	global_load_dwordx4 v[40:43], v[40:41], off nt
	ds_read2st64_b32 v[204:205], v89 offset0:28 offset1:30
	s_waitcnt lgkmcnt(1)
	v_mul_f32_e32 v192, 0x3e000000, v191
	ds_read2_b32 v[82:83], v65 offset0:3 offset1:131
	s_waitcnt vmcnt(14)
	v_pk_mul_f32 v[62:63], v[62:63], v[192:193] op_sel_hi:[1,0]
	v_pk_mul_f32 v[60:61], v[60:61], v[192:193] op_sel_hi:[1,0]
	ds_read2st64_b32 v[192:193], v89 offset0:8 offset1:10
	s_waitcnt lgkmcnt(2)
	v_mul_f32_e32 v204, 0x3e000000, v204
	v_mul_f32_e32 v190, 0x3e000000, v190
	s_waitcnt lgkmcnt(1)
	v_mul_f32_e32 v188, 0x3e000000, v83
	v_mul_f32_e32 v82, 0x3e000000, v82
	s_waitcnt lgkmcnt(0)
	v_mul_f32_e32 v192, 0x3e000000, v192
	v_mul_f32_e32 v194, 0x3e000000, v193
	s_waitcnt vmcnt(11)
	v_pk_mul_f32 v[50:51], v[50:51], v[196:197] op_sel_hi:[1,0]
	v_pk_mul_f32 v[48:49], v[48:49], v[196:197] op_sel_hi:[1,0]
	v_mul_f32_e32 v196, 0x3e000000, v197
	s_waitcnt vmcnt(10)
	v_pk_mul_f32 v[58:59], v[58:59], v[196:197] op_sel_hi:[1,0]
	v_pk_mul_f32 v[56:57], v[56:57], v[196:197] op_sel_hi:[1,0]
	ds_read2st64_b32 v[196:197], v89 offset0:16 offset1:18
	s_waitcnt lgkmcnt(0)
	v_mul_f32_e32 v196, 0x3e000000, v196
	v_mul_f32_e32 v198, 0x3e000000, v197
	s_waitcnt vmcnt(7)
	v_pk_mul_f32 v[46:47], v[46:47], v[200:201] op_sel_hi:[1,0]
	v_pk_mul_f32 v[44:45], v[44:45], v[200:201] op_sel_hi:[1,0]
	v_mul_f32_e32 v200, 0x3e000000, v201
	s_waitcnt vmcnt(6)
	v_pk_mul_f32 v[54:55], v[54:55], v[200:201] op_sel_hi:[1,0]
	v_pk_mul_f32 v[52:53], v[52:53], v[200:201] op_sel_hi:[1,0]
	ds_read2st64_b32 v[200:201], v89 offset0:24 offset1:26
	s_waitcnt lgkmcnt(0)
	v_mul_f32_e32 v200, 0x3e000000, v200
	v_mul_f32_e32 v202, 0x3e000000, v201
	s_waitcnt vmcnt(3)
	v_pk_mul_f32 v[38:39], v[38:39], v[204:205] op_sel_hi:[1,0]
	v_pk_mul_f32 v[36:37], v[36:37], v[204:205] op_sel_hi:[1,0]
	v_mul_f32_e32 v204, 0x3e000000, v205
	s_waitcnt vmcnt(1)
	v_pk_mul_f32 v[10:11], v[10:11], v[190:191] op_sel_hi:[1,0]
	v_pk_mul_f32 v[8:9], v[8:9], v[190:191] op_sel_hi:[1,0]
	s_waitcnt vmcnt(0)
	v_pk_mul_f32 v[40:41], v[40:41], v[204:205] op_sel_hi:[1,0]
	v_pk_mul_f32 v[42:43], v[42:43], v[204:205] op_sel_hi:[1,0]
	v_pk_fma_f32 v[190:191], v[6:7], v[82:83], v[10:11] op_sel_hi:[1,0,1]
	v_pk_fma_f32 v[204:205], v[4:5], v[82:83], v[8:9] op_sel_hi:[1,0,1]
	v_pk_fma_f32 v[6:7], v[6:7], v[82:83], v[10:11] op_sel_hi:[1,0,1] neg_lo:[0,0,1] neg_hi:[0,0,1]
	v_pk_fma_f32 v[4:5], v[4:5], v[82:83], v[8:9] op_sel_hi:[1,0,1] neg_lo:[0,0,1] neg_hi:[0,0,1]
	v_pk_fma_f32 v[8:9], v[2:3], v[188:189], v[62:63] op_sel_hi:[1,0,1]
	v_pk_fma_f32 v[10:11], v[0:1], v[188:189], v[60:61] op_sel_hi:[1,0,1]
	v_pk_fma_f32 v[2:3], v[2:3], v[188:189], v[62:63] op_sel_hi:[1,0,1] neg_lo:[0,0,1] neg_hi:[0,0,1]
	v_pk_fma_f32 v[0:1], v[0:1], v[188:189], v[60:61] op_sel_hi:[1,0,1] neg_lo:[0,0,1] neg_hi:[0,0,1]
	v_pk_fma_f32 v[60:61], v[18:19], v[192:193], v[50:51] op_sel_hi:[1,0,1]
	v_pk_fma_f32 v[62:63], v[16:17], v[192:193], v[48:49] op_sel_hi:[1,0,1]
	v_pk_fma_f32 v[18:19], v[18:19], v[192:193], v[50:51] op_sel_hi:[1,0,1] neg_lo:[0,0,1] neg_hi:[0,0,1]
	v_pk_fma_f32 v[16:17], v[16:17], v[192:193], v[48:49] op_sel_hi:[1,0,1] neg_lo:[0,0,1] neg_hi:[0,0,1]
	v_pk_fma_f32 v[48:49], v[14:15], v[194:195], v[58:59] op_sel_hi:[1,0,1]
	v_pk_fma_f32 v[50:51], v[12:13], v[194:195], v[56:57] op_sel_hi:[1,0,1]
	v_pk_fma_f32 v[14:15], v[14:15], v[194:195], v[58:59] op_sel_hi:[1,0,1] neg_lo:[0,0,1] neg_hi:[0,0,1]
	v_pk_fma_f32 v[12:13], v[12:13], v[194:195], v[56:57] op_sel_hi:[1,0,1] neg_lo:[0,0,1] neg_hi:[0,0,1]
	v_pk_fma_f32 v[56:57], v[26:27], v[196:197], v[46:47] op_sel_hi:[1,0,1]
	v_pk_fma_f32 v[58:59], v[24:25], v[196:197], v[44:45] op_sel_hi:[1,0,1]
	v_pk_fma_f32 v[26:27], v[26:27], v[196:197], v[46:47] op_sel_hi:[1,0,1] neg_lo:[0,0,1] neg_hi:[0,0,1]
	v_pk_fma_f32 v[24:25], v[24:25], v[196:197], v[44:45] op_sel_hi:[1,0,1] neg_lo:[0,0,1] neg_hi:[0,0,1]
	v_pk_fma_f32 v[44:45], v[22:23], v[198:199], v[54:55] op_sel_hi:[1,0,1]
	v_pk_fma_f32 v[46:47], v[20:21], v[198:199], v[52:53] op_sel_hi:[1,0,1]
	v_pk_fma_f32 v[22:23], v[22:23], v[198:199], v[54:55] op_sel_hi:[1,0,1] neg_lo:[0,0,1] neg_hi:[0,0,1]
	v_pk_fma_f32 v[20:21], v[20:21], v[198:199], v[52:53] op_sel_hi:[1,0,1] neg_lo:[0,0,1] neg_hi:[0,0,1]
	v_pk_fma_f32 v[52:53], v[34:35], v[200:201], v[38:39] op_sel_hi:[1,0,1]
	v_pk_fma_f32 v[54:55], v[32:33], v[200:201], v[36:37] op_sel_hi:[1,0,1]
	v_pk_fma_f32 v[34:35], v[34:35], v[200:201], v[38:39] op_sel_hi:[1,0,1] neg_lo:[0,0,1] neg_hi:[0,0,1]
	v_pk_fma_f32 v[38:39], v[28:29], v[202:203], v[40:41] op_sel_hi:[1,0,1]
	v_pk_fma_f32 v[32:33], v[32:33], v[200:201], v[36:37] op_sel_hi:[1,0,1] neg_lo:[0,0,1] neg_hi:[0,0,1]
	v_pk_fma_f32 v[36:37], v[30:31], v[202:203], v[42:43] op_sel_hi:[1,0,1]
	v_pk_fma_f32 v[30:31], v[30:31], v[202:203], v[42:43] op_sel_hi:[1,0,1] neg_lo:[0,0,1] neg_hi:[0,0,1]
	v_pk_fma_f32 v[28:29], v[28:29], v[202:203], v[40:41] op_sel_hi:[1,0,1] neg_lo:[0,0,1] neg_hi:[0,0,1]
	v_pk_add_f32 v[42:43], v[204:205], v[62:63]
	v_pk_add_f32 v[188:189], v[10:11], v[50:51]
	v_sub_f32_e32 v11, v11, v51
	v_sub_f32_e32 v10, v10, v50
	v_pk_add_f32 v[50:51], v[4:5], v[16:17]
	v_sub_f32_e32 v5, v5, v17
	v_sub_f32_e32 v4, v4, v16
	v_pk_add_f32 v[16:17], v[2:3], v[14:15]
	v_sub_f32_e32 v3, v3, v15
	v_sub_f32_e32 v2, v2, v14
	v_pk_add_f32 v[14:15], v[58:59], v[54:55]
	v_sub_f32_e32 v55, v59, v55
	v_sub_f32_e32 v54, v58, v54
	v_pk_add_f32 v[58:59], v[46:47], v[38:39]
	v_pk_add_f32 v[40:41], v[190:191], v[60:61]
	v_pk_add_f32 v[82:83], v[8:9], v[48:49]
	v_sub_f32_e32 v9, v9, v49
	v_sub_f32_e32 v8, v8, v48
	v_pk_add_f32 v[48:49], v[6:7], v[18:19]
	v_sub_f32_e32 v7, v7, v19
	v_sub_f32_e32 v6, v6, v18
	v_pk_add_f32 v[18:19], v[0:1], v[12:13]
	v_sub_f32_e32 v1, v1, v13
	v_sub_f32_e32 v0, v0, v12
	v_pk_add_f32 v[12:13], v[56:57], v[52:53]
	v_sub_f32_e32 v53, v57, v53
	v_sub_f32_e32 v52, v56, v52
	v_pk_add_f32 v[56:57], v[44:45], v[36:37]
	v_sub_f32_e32 v37, v45, v37
	v_sub_f32_e32 v36, v44, v36
	v_sub_f32_e32 v39, v47, v39
	v_sub_f32_e32 v38, v46, v38
	v_pk_add_f32 v[44:45], v[26:27], v[34:35]
	v_pk_add_f32 v[46:47], v[24:25], v[32:33]
	v_sub_f32_e32 v27, v27, v35
	v_sub_f32_e32 v26, v26, v34
	v_sub_f32_e32 v25, v25, v33
	v_sub_f32_e32 v24, v24, v32
	v_pk_add_f32 v[32:33], v[22:23], v[30:31]
	v_pk_add_f32 v[34:35], v[20:21], v[28:29]
	v_sub_f32_e32 v23, v23, v31
	v_sub_f32_e32 v22, v22, v30
	v_pk_add_f32 v[30:31], v[42:43], v[14:15]
	v_sub_f32_e32 v192, v42, v14
	v_sub_f32_e32 v193, v43, v15
	v_pk_add_f32 v[14:15], v[188:189], v[58:59]
	v_sub_f32_e32 v61, v191, v61
	v_sub_f32_e32 v60, v190, v60
	v_sub_f32_e32 v63, v205, v63
	v_sub_f32_e32 v62, v204, v62
	v_sub_f32_e32 v21, v21, v29
	v_sub_f32_e32 v20, v20, v28
	v_pk_add_f32 v[28:29], v[40:41], v[12:13]
	v_sub_f32_e32 v190, v40, v12
	v_sub_f32_e32 v191, v41, v13
	v_pk_add_f32 v[12:13], v[82:83], v[56:57]
	v_sub_f32_e32 v57, v83, v57
	v_sub_f32_e32 v56, v82, v56
	v_sub_f32_e32 v59, v189, v59
	v_sub_f32_e32 v58, v188, v58
	v_pk_add_f32 v[40:41], v[48:49], v[44:45]
	v_pk_add_f32 v[42:43], v[50:51], v[46:47]
	v_sub_f32_e32 v82, v48, v44
	v_sub_f32_e32 v83, v49, v45
	v_sub_f32_e32 v188, v50, v46
	v_sub_f32_e32 v189, v51, v47
	v_pk_add_f32 v[44:45], v[16:17], v[32:33]
	v_pk_add_f32 v[46:47], v[18:19], v[34:35]
	v_sub_f32_e32 v195, v16, v32
	v_max3_f32 v16, v187, |v30|, |v14|
	v_sub_f32_e32 v196, v19, v35
	v_sub_f32_e32 v197, v18, v34
	v_pk_add_f32 v[48:49], v[60:61], v[52:53]
	v_pk_add_f32 v[50:51], v[62:63], v[54:55]
	v_sub_f32_e32 v60, v60, v52
	v_sub_f32_e32 v61, v61, v53
	v_sub_f32_e32 v62, v62, v54
	v_sub_f32_e32 v63, v63, v55
	v_pk_add_f32 v[52:53], v[8:9], v[36:37]
	v_pk_add_f32 v[54:55], v[10:11], v[38:39]
	v_sub_f32_e32 v37, v9, v37
	v_sub_f32_e32 v198, v8, v36
	v_sub_f32_e32 v39, v11, v39
	v_sub_f32_e32 v38, v10, v38
	v_pk_add_f32 v[8:9], v[6:7], v[26:27]
	v_pk_add_f32 v[10:11], v[4:5], v[24:25]
	v_sub_f32_e32 v199, v6, v26
	v_sub_f32_e32 v200, v7, v27
	v_sub_f32_e32 v201, v4, v24
	v_sub_f32_e32 v202, v5, v25
	v_pk_add_f32 v[4:5], v[2:3], v[22:23]
	v_pk_add_f32 v[6:7], v[0:1], v[20:21]
	v_sub_f32_e32 v2, v2, v22
	v_sub_f32_e32 v1, v1, v21
	v_sub_f32_e32 v0, v0, v20
	v_cvt_pk_bf16_f32 v36, v30, v31
	v_cvt_pk_bf16_f32 v19, v28, v29
	v_max3_f32 v20, v186, |v31|, |v15|
	v_max3_f32 v21, v185, |v28|, |v12|
	v_max3_f32 v22, v79, |v29|, |v13|
	v_cvt_pk_bf16_f32 v35, v14, v15
	v_cvt_pk_bf16_f32 v18, v12, v13
	v_max3_f32 v12, v16, |v42|, |v46|
	v_max3_f32 v13, v20, |v43|, |v47|
	v_max3_f32 v14, v21, |v40|, |v44|
	v_max3_f32 v20, v22, |v41|, |v45|
	v_max3_f32 v12, v12, |v50|, |v54|
	v_sub_f32_e32 v194, v17, v33
	v_cvt_pk_bf16_f32 v34, v42, v43
	v_cvt_pk_bf16_f32 v17, v40, v41
	v_cvt_pk_bf16_f32 v33, v46, v47
	v_cvt_pk_bf16_f32 v16, v44, v45
	v_cvt_pk_bf16_f32 v32, v50, v51
	v_cvt_pk_bf16_f32 v15, v48, v49
	v_max3_f32 v22, v14, |v48|, |v52|
	v_max3_f32 v20, v20, |v49|, |v53|
	v_cvt_pk_bf16_f32 v31, v54, v55
	v_cvt_pk_bf16_f32 v14, v52, v53
	v_cvt_pk_bf16_f32 v30, v10, v11
	v_max3_f32 v10, v12, |v10|, |v6|
	v_max3_f32 v21, v13, |v51|, |v55|
	v_cvt_pk_bf16_f32 v13, v8, v9
	v_max3_f32 v8, v22, |v8|, |v4|
	v_max3_f32 v9, v20, |v9|, |v5|
	v_cvt_pk_bf16_f32 v29, v6, v7
	v_cvt_pk_bf16_f32 v12, v4, v5
	v_max3_f32 v4, v10, |v192|, |v58|
	v_max3_f32 v21, v21, |v11|, |v7|
	v_max3_f32 v7, v9, |v191|, |v57|
	v_max3_f32 v4, v4, |v188|, |v197|
	v_sub_f32_e32 v3, v3, v23
	v_max3_f32 v5, v21, |v193|, |v59|
	v_max3_f32 v6, v8, |v190|, |v56|
	v_max3_f32 v20, v7, |v83|, |v194|
	v_max3_f32 v23, v4, |v62|, |v38|
	v_max3_f32 v5, v5, |v189|, |v196|
	v_max3_f32 v6, v6, |v82|, |v195|
	v_max3_f32 v20, v20, |v61|, |v37|
	v_max3_f32 v23, v23, |v201|, |v0|
	v_cvt_pk_bf16_f32 v28, v192, v193
	v_cvt_pk_bf16_f32 v11, v190, v191
	v_cvt_pk_bf16_f32 v27, v58, v59
	v_cvt_pk_bf16_f32 v10, v56, v57
	v_cvt_pk_bf16_f32 v26, v188, v189
	v_cvt_pk_bf16_f32 v9, v82, v83
	v_cvt_pk_bf16_f32 v25, v197, v196
	v_cvt_pk_bf16_f32 v8, v195, v194
	v_cvt_pk_bf16_f32 v24, v62, v63
	v_cvt_pk_bf16_f32 v7, v60, v61
	v_max3_f32 v5, v5, |v63|, |v39|
	v_max3_f32 v40, v6, |v60|, |v198|
	v_cvt_pk_bf16_f32 v22, v38, v39
	v_cvt_pk_bf16_f32 v6, v198, v37
	v_cvt_pk_bf16_f32 v21, v201, v202
	v_cvt_pk_bf16_f32 v4, v199, v200
	v_max3_f32 v39, v20, |v200|, |v3|
	v_cvt_pk_bf16_f32 v20, v0, v1
	ds_swizzle_b32 v0, v23 offset:swizzle(SWAP,8)
	v_max3_f32 v37, v5, |v202|, |v1|
	ds_swizzle_b32 v1, v37 offset:swizzle(SWAP,8)
	v_max3_f32 v38, v40, |v199|, |v2|
	v_cvt_pk_bf16_f32 v5, v2, v3
	s_waitcnt lgkmcnt(1)
	v_max_f32_e32 v0, v0, v0
	v_max_f32_e32 v0, v23, v0
	ds_swizzle_b32 v23, v0 offset:swizzle(SWAP,16)
	s_waitcnt lgkmcnt(1)
	v_max_f32_e32 v1, v1, v1
	v_max_f32_e32 v1, v37, v1
	ds_swizzle_b32 v2, v38 offset:swizzle(SWAP,8)
	ds_swizzle_b32 v3, v39 offset:swizzle(SWAP,8)
	s_waitcnt lgkmcnt(2)
	v_max_f32_e32 v23, v23, v23
	v_max_f32_e32 v0, v0, v23
	ds_swizzle_b32 v23, v1 offset:swizzle(SWAP,16)
	s_waitcnt lgkmcnt(2)
	v_max_f32_e32 v2, v2, v2
	v_max_f32_e32 v2, v38, v2
	s_waitcnt lgkmcnt(1)
	v_max_f32_e32 v3, v3, v3
	v_max_f32_e32 v3, v39, v3
	s_waitcnt lgkmcnt(0)
	v_max_f32_e32 v23, v23, v23
	v_max_f32_e32 v1, v1, v23
	ds_swizzle_b32 v23, v2 offset:swizzle(SWAP,16)
	v_mov_b32_e32 v37, v1
	s_nop 1
	v_permlane32_swap_b32_e32 v1, v37
	s_waitcnt lgkmcnt(0)
	v_max_f32_e32 v23, v23, v23
	v_max_f32_e32 v2, v2, v23
	ds_swizzle_b32 v23, v3 offset:swizzle(SWAP,16)
	v_mov_b32_e32 v38, v2
	s_nop 1
	v_permlane32_swap_b32_e32 v2, v38
	s_waitcnt lgkmcnt(0)
	v_max_f32_e32 v23, v23, v23
	v_max_f32_e32 v3, v3, v23
	v_mov_b32_e32 v23, v0
	v_mov_b32_e32 v39, v3
	s_nop 0
	v_permlane32_swap_b32_e32 v0, v23
	v_permlane32_swap_b32_e32 v3, v39
	s_and_saveexec_b64 s[28:29], s[4:5]
	s_cbranch_execz .LBB0_25
	v_max_f32_e32 v0, v0, v0
	v_max_f32_e32 v23, v23, v23
	v_max_f32_e32 v0, v0, v23
	v_max_f32_e32 v1, v1, v1
	v_max_f32_e32 v23, v37, v37
	v_max_f32_e32 v1, v1, v23
	v_max_f32_e32 v2, v2, v2
	v_max_f32_e32 v23, v38, v38
	v_max_f32_e32 v2, v2, v23
	v_max_f32_e32 v3, v3, v3
	v_max_f32_e32 v23, v39, v39
	v_max_f32_e32 v3, v3, v23
	ds_write_b128 v85, v[0:3]

.LBB0_34:
	v_readlane_b32 s4, v247, 0
	s_mul_hi_u32 s4, s4, 0x200
	s_mul_i32 s4, s4, s65
	s_sub_i32 s4, 0x200, s4
	s_sub_i32 s5, s4, s65
	s_cmp_ge_u32 s4, s65
	s_cselect_b32 s4, s5, s4
	s_sub_i32 s5, s4, s65
	s_cmp_ge_u32 s4, s65
	s_cselect_b32 s4, s5, s4
	s_sub_i32 s5, s64, s4
	s_cmp_lg_u32 s4, 0
	s_cselect_b32 s8, s5, 0
	s_cmpk_lt_i32 s8, 0x15c
	s_mul_i32 s5, s8, 53
	s_cselect_b32 s34, s5, 0
	s_mul_i32 s5, s3, 0x2100
	s_add_i32 s5, s5, 0
	s_load_dwordx2 s[22:23], s[20:21], 0x18
	s_load_dwordx2 s[24:25], s[20:21], 0x78
	s_add_u32 s20, s18, 0x400000
	s_addc_u32 s21, s19, 0
	s_add_u32 s26, s18, 0x11800000
	s_addc_u32 s27, s19, 0
	s_add_u32 s28, s18, 0x78000
	s_addc_u32 s29, s19, 0
	s_cmp_lt_i32 s34, 1
	s_cselect_b64 s[6:7], -1, 0
	s_cmp_lt_i32 s2, s4
	s_cselect_b64 s[10:11], -1, 0
	s_or_b64 s[6:7], s[6:7], s[10:11]
	s_and_b64 vcc, exec, s[6:7]
	v_writelane_b32 v247, s5, 3
	s_cbranch_vccnz .LBB0_84
	s_sub_i32 s4, s2, s4
	s_lshl_b32 s9, s4, 3
	s_add_i32 s9, s9, s3
	s_cmp_ge_i32 s9, s34
	s_cbranch_scc1 .LBB0_84
	s_cmpk_gt_i32 s9, 0x47ff
	s_cbranch_scc0 .LBB0_39
	s_add_i32 s4, s9, 0xffffb800
	s_lshr_b32 s4, s4, 1
	s_and_b32 s42, s4, 0x7fffffc0
	s_lshl_b32 s4, s9, 5
	s_and_b32 s36, s4, 0xfe0
	s_waitcnt lgkmcnt(0)
	s_mov_b64 s[4:5], s[24:25]
	s_mov_b32 s43, 1
	s_cbranch_execz .LBB0_40
	s_mov_b64 s[6:7], 0x1000
	s_movk_i32 s67, 0x2b00
	v_mov_b32_e32 v70, 0x3d000000
	s_mov_b64 s[48:49], s[26:27]
	s_mov_b64 s[38:39], s[28:29]
	s_branch .LBB0_41

.LBB0_236:
	v_readlane_b32 s4, v247, 0
	s_mul_hi_u32 s4, s4, 0xda4
	s_mul_i32 s4, s4, s65
	s_sub_i32 s4, 0xda4, s4
	s_sub_i32 s5, s4, s65
	s_cmp_ge_u32 s4, s65
	s_cselect_b32 s4, s5, s4
	s_sub_i32 s5, s4, s65
	s_cmp_ge_u32 s4, s65
	s_cselect_b32 s10, s5, s4
	s_cmp_eq_u32 s10, 0
	s_cselect_b64 s[4:5], -1, 0
	s_cmp_ge_i32 s66, s10
	s_cselect_b64 s[8:9], -1, 0
	s_or_b64 s[14:15], s[8:9], s[4:5]
	s_andn2_b64 vcc, exec, s[14:15]
	s_cbranch_vccnz .LBB0_245
	s_xor_b64 s[4:5], s[4:5], -1
	s_and_b64 s[4:5], s[8:9], s[4:5]
	s_and_b64 s[4:5], s[4:5], exec
	s_cselect_b32 s4, s10, 0
	s_mov_b32 s8, 0
	s_sub_i32 s5, s66, s4
	s_add_i32 s20, s5, 0x180
	v_mbcnt_lo_u32_b32 v0, -1, s8
	v_mbcnt_hi_u32_b32 v0, -1, v0
	s_cmpk_gt_i32 s20, 0x2af
	s_cbranch_scc1 .LBB0_245
	v_lshlrev_b32_e32 v1, 3, v0
	v_and_b32_e32 v2, 0xffffffc0, v1
	s_sub_i32 s21, s64, s4
	v_add_u32_e32 v1, s63, v2
	s_mov_b32 s4, 0xac00
	v_mad_i64_i32 v[64:65], s[4:5], v1, s4, 0
	v_lshlrev_b32_e32 v1, 2, v0
	v_and_b32_e32 v66, 28, v1
	s_load_dwordx4 s[8:11], s[6:7], 0x68
	v_cmp_gt_u32_e64 s[4:5], 8, v0
	v_lshlrev_b32_e32 v68, 2, v66
	s_add_i32 s6, 0, 0x16000
	v_mov_b32_e32 v69, 0
	s_waitcnt vmcnt(0)
	v_add_u32_e32 v76, s6, v68
	s_and_b64 s[6:7], s[40:41], s[4:5]
	s_waitcnt lgkmcnt(0)
	v_lshl_add_u64 v[0:1], s[12:13], 0, v[68:69]
	s_add_u32 s12, s12, s63
	s_mov_b64 s[14:15], 0xa0000
	s_addc_u32 s13, s13, 0
	v_ashrrev_i32_e32 v3, 31, v2
	v_writelane_b32 v247, s84, 1
	v_lshl_add_u64 v[70:71], v[0:1], 0, s[14:15]
	v_lshl_add_u64 v[0:1], s[12:13], 0, v[2:3]
	s_mov_b64 s[12:13], 0x6c00000
	v_writelane_b32 v247, s85, 2
	v_add_u32_e32 v67, s72, v68
	v_lshl_add_u64 v[72:73], v[0:1], 0, s[12:13]
	v_lshlrev_b32_e32 v68, 2, v66
	s_mov_b32 s13, 0x2b000
	s_mov_b32 s22, 0x35000
	s_mov_b32 s23, 0x40000
	s_mov_b32 s24, 0x4b000
	s_mov_b32 s25, 0x56000
	s_mov_b32 s26, 0x60000
	s_mov_b32 s27, 0x6b000
	s_mov_b32 s28, 0x76000
	s_mov_b32 s29, 0x81000
	s_mov_b32 s30, 0x8b000
	s_mov_b32 s31, 0x96000
	s_mov_b32 s34, 0xa1000
	s_mov_b32 s35, 0xac000
	s_mov_b32 s36, 0xb6000
	s_mov_b32 s37, 0xc1000
	s_mov_b32 s38, 0xcc000
	s_mov_b32 s39, 0xd7000
	s_mov_b32 s45, 0xe1000
	s_mov_b32 s46, 0xec000
	s_mov_b32 s47, 0xf7000
	s_mov_b32 s48, 0x102000
	s_mov_b32 s49, 0x10c000
	s_mov_b32 s50, 0x117000
	s_mov_b32 s51, 0x122000
	s_mov_b32 s52, 0x12d000
	s_mov_b32 s53, 0x137000
	s_mov_b32 s54, 0x142000
	s_mov_b32 s55, 0x14d000
	s_mov_b32 s56, 0x158000
	s_mov_b32 s57, 0x162000
	s_mov_b32 s58, 0x16d000
	s_mov_b32 s59, 0x178000
	s_mov_b32 s60, 0x183000
	s_mov_b32 s61, 0x18d000
	s_mov_b32 s62, 0x198000
	s_mov_b32 s63, 0x1a3000
	s_mov_b32 s68, 0x1ae000
	s_mov_b32 s69, 0x1b8000
	s_mov_b32 s70, 0x1c3000
	s_mov_b32 s71, 0x1ce000
	s_mov_b32 s72, 0x1d9000
	s_mov_b32 s73, 0x1e3000
	s_mov_b32 s74, 0x1ee000
	s_mov_b32 s75, 0x1f9000
	s_mov_b32 s76, 0x204000
	s_mov_b32 s77, 0x20e000
	s_mov_b32 s78, 0x219000
	s_mov_b32 s79, 0x224000
	s_mov_b32 s80, 0x22f000
	s_mov_b32 s81, 0x239000
	s_mov_b32 s82, 0x244000
	s_mov_b32 s83, 0x24f000
	s_mov_b32 s84, 0x25a000
	s_mov_b32 s85, 0x264000
	s_mov_b32 s86, 0x26f000
	s_mov_b32 s87, 0x27a000
	s_mov_b32 s88, 0x285000
	s_mov_b32 s89, 0x28f000
	s_mov_b32 s90, 0x29a000
	s_mov_b32 s91, 0x2a5000
	s_mov_b32 s12, 0x3f808000
	s_mov_b32 s92, 0x42fe0000
	s_mov_b32 s93, 0xc0c0400
	s_mov_b32 s94, 0x5040100
	s_movk_i32 s95, 0x1000
	s_movk_i32 s96, 0x2000
	s_movk_i32 s97, 0x3000
	s_branch .LBB0_240
